# attention K/V staging: issue each chunk's K, rope and V loads together (k_gain kept in registers, ctx K loads hoisted before the barrier) instead of one load per round trip; also dropped conservative
# speedup vs baseline: 1.0051x; 1.0034x over previous
; #define LAS __attribute__((address_space(3)))
; __device__ __forceinline__ unsigned pk2(float lo, float hi) { unsigned r; asm("v_cvt_pk_bf16_f32 %0, %1, %2" : "=v"(r) : "v"(lo), "v"(hi)); return r; }
; __device__ __forceinline__ float bflo(unsigned u) { return __uint_as_float(u << 16); }
; __device__ __forceinline__ void attn_stage(LAS unsigned char* Kl, LAS unsigned char* Vl, const bf16_t* qk, const bf16_t* Vt, int tok0, int g, int tid, const float* kgain, const float2* rope, bool do_rope) {
;     const int row = tid >> 3, piece = tid & 7;
;     const u32x4 kraw = *(const u32x4*)(qk + (size_t)(tok0 + row) * 1280 + 1024 + 64 * g + 8 * piece);
;     float y[8] = {bflo(kraw.x), bfhi(kraw.x), bflo(kraw.y), bfhi(kraw.y), bflo(kraw.z), bfhi(kraw.z), bflo(kraw.w), bfhi(kraw.w)};
;     float ss = 0.f;
; #pragma unroll
;     for (int i = 0; i < 8; ++i) ss += y[i] * y[i];
;     ss += __shfl_xor(ss, 1); ss += __shfl_xor(ss, 2); ss += __shfl_xor(ss, 4);
;     const float rs = rsqrtf(ss * (1.f / 64.f) + 1e-6f);
;     const f32x4 g0 = *(const f32x4*)(kgain + 8 * piece), g1 = *(const f32x4*)(kgain + 8 * piece + 4);
; #pragma unroll
;     for (int i = 0; i < 4; ++i) { y[i] *= rs * g0[i]; y[4 + i] *= rs * g1[i]; }
;     float py[8];
; #pragma unroll
;     for (int i = 0; i < 8; ++i) py[i] = __shfl_xor(y[i], 2);
;     if (do_rope) {
;         const int token = tok0 + row, pos = (piece < 4) ? (token >> 6) : (token & 63);
;         const float2* cs = rope + pos * 16 + 8 * (piece & 1);
; #pragma unroll
;         for (int i = 0; i < 8; ++i) { const float2 t = cs[i]; y[i] = (piece & 2) ? (py[i] * t.y + y[i] * t.x) : (y[i] * t.x - py[i] * t.y); }
;     }
;     u32x4 kv; kv.x = pk2(y[0], y[1]); kv.y = pk2(y[2], y[3]); kv.z = pk2(y[4], y[5]); kv.w = pk2(y[6], y[7]);
;     *(LAS u32x4*)(Kl + row * 144 + piece * 16) = kv;
;     const u32x4 vv = *(const u32x4*)(Vt + (size_t)(g * 64 + row) * MTOT + tok0 + 8 * piece);
;     LAS u32x2* vd = (LAS u32x2*)(Vl + row * 136 + piece * 16); vd[0] = (u32x2){vv.x, vv.y}; vd[1] = (u32x2){vv.z, vv.w};
; __device__ __forceinline__ void attn_phase(const Params& P, LAS unsigned char* lds) {
;     ...
;         __syncthreads();
; #pragma unroll
;         for (int ci = 0; ci < 4; ++ci) attn_stage(lds + ci * KSZ, lds + VBASE + ci * VSZ, qk, Vt, SEQ + 64 * ci, g, tid, P.k_gain, rope, false);
.LBB0_723:
	v_readlane_b32 s8, v252, 30
	v_readlane_b32 s9, v252, 31
	s_lshl_b32 s8, s35, 1
	s_nop 0
	v_lshl_add_u64 v[34:35], v[94:95], 0, s[8:9]
	global_load_dwordx4 v[230:233], v[34:35], off offset:2048
	v_lshl_add_u64 v[246:247], v[96:97], 0, s[8:9]
	global_load_dwordx4 v[234:237], v[246:247], off offset:2048
	v_lshl_add_u64 v[246:247], v[98:99], 0, s[8:9]
	global_load_dwordx4 v[238:241], v[246:247], off offset:2048
	v_lshl_add_u64 v[246:247], v[100:101], 0, s[8:9]
	global_load_dwordx4 v[242:245], v[246:247], off offset:2048
	s_barrier
	s_nop 0
	s_mov_b32 s2, 0x800000
	s_mov_b32 s0, 0x8000
	v_mov_b32_e32 v175, v1
	s_mov_b32 s1, s9
	v_ashrrev_i32_e32 v109, 31, v108
	s_movk_i32 s48, 0x7000
	s_waitcnt vmcnt(0)
	v_mov_b64_e32 v[34:35], v[230:231]
	v_mov_b64_e32 v[36:37], v[232:233]
	v_lshlrev_b32_e32 v42, 16, v34
	v_and_b32_e32 v43, 0xffff0000, v34
	v_pk_mul_f32 v[38:39], v[42:43], v[42:43]
	v_and_b32_e32 v44, 0xffff0000, v35
	v_lshlrev_b32_e32 v45, 16, v35
	v_pk_mul_f32 v[34:35], v[44:45], v[44:45]
	v_add_f32_e32 v38, v38, v39
	v_and_b32_e32 v46, 0xffff0000, v36
	v_lshlrev_b32_e32 v47, 16, v36
	v_add_f32_e32 v35, v35, v38
	v_pk_mul_f32 v[40:41], v[46:47], v[46:47]
	v_add_f32_e32 v34, v34, v35
	v_and_b32_e32 v48, 0xffff0000, v37
	v_lshlrev_b32_e32 v49, 16, v37
	v_add_f32_e32 v34, v41, v34
	v_pk_mul_f32 v[36:37], v[48:49], v[48:49]
	v_add_f32_e32 v34, v40, v34
	v_add_f32_e32 v34, v37, v34
	v_add_f32_e32 v34, v36, v34
	ds_bpermute_b32 v35, v180, v34
	s_waitcnt lgkmcnt(0)
	v_add_f32_e32 v34, v34, v35
	ds_bpermute_b32 v35, v181, v34
	s_waitcnt lgkmcnt(0)
	v_add_f32_e32 v34, v34, v35
	ds_bpermute_b32 v35, v182, v34
	s_waitcnt lgkmcnt(0)
	v_add_f32_e32 v34, v34, v35
	v_fmamk_f32 v34, v34, 0x3c800000, v197
	v_cmp_gt_f32_e32 vcc, s2, v34
	v_mul_f32_e32 v35, 0x4b800000, v34
	s_nop 0
	v_cndmask_b32_e32 v34, v34, v35, vcc
	v_rsq_f32_e32 v34, v34
	s_nop 0
	v_mul_f32_e32 v35, 0x45800000, v34
	v_cndmask_b32_e32 v50, v34, v35, vcc
	v_mov_b64_e32 v[34:35], v[222:223]
	v_mov_b64_e32 v[36:37], v[224:225]
	v_mov_b64_e32 v[38:39], v[226:227]
	v_mov_b64_e32 v[40:41], v[228:229]
	v_mul_f32_e32 v51, v38, v50
	v_mul_f32_e32 v42, v51, v42
	v_mul_f32_e32 v51, v34, v50
	v_mul_f32_e32 v47, v51, v47
	v_mul_f32_e32 v51, v39, v50
	v_mul_f32_e32 v43, v51, v43
	v_mul_f32_e32 v51, v35, v50
	v_mul_f32_e32 v46, v51, v46
	v_mul_f32_e32 v51, v40, v50
	v_mul_f32_e32 v45, v51, v45
	v_mul_f32_e32 v51, v36, v50
	v_mul_f32_e32 v49, v51, v49
	v_mul_f32_e32 v51, v41, v50
	v_mul_f32_e32 v44, v51, v44
	v_mul_f32_e32 v50, v37, v50
	v_cvt_pk_bf16_f32 v42, v42, v43
	v_mul_f32_e32 v48, v50, v48
	v_cvt_pk_bf16_f32 v43, v45, v44
	v_cvt_pk_bf16_f32 v44, v47, v46
	v_cvt_pk_bf16_f32 v45, v49, v48
	ds_write_b128 v107, v[42:45]
	v_add_co_u32_e32 v42, vcc, s0, v112
	v_writelane_b32 v252, s0, 30
	s_nop 0
	v_addc_co_u32_e32 v43, vcc, 0, v113, vcc
	global_load_dwordx4 v[44:47], v[42:43], off
	v_writelane_b32 v252, s1, 31
	s_waitcnt vmcnt(0)
	ds_write2_b64 v186, v[44:45], v[46:47] offset1:1
	v_mov_b64_e32 v[44:45], v[234:235]
	v_mov_b64_e32 v[46:47], v[236:237]
	v_lshlrev_b32_e32 v48, 16, v44
	v_and_b32_e32 v49, 0xffff0000, v44
	v_pk_mul_f32 v[50:51], v[48:49], v[48:49]
	v_and_b32_e32 v44, 0xffff0000, v45
	v_lshlrev_b32_e32 v45, 16, v45
	v_pk_mul_f32 v[52:53], v[44:45], v[44:45]
	v_add_f32_e32 v50, v50, v51
	v_and_b32_e32 v54, 0xffff0000, v46
	v_lshlrev_b32_e32 v55, 16, v46
	v_add_f32_e32 v50, v53, v50
	v_pk_mul_f32 v[56:57], v[54:55], v[54:55]
	v_add_f32_e32 v50, v52, v50
	v_and_b32_e32 v46, 0xffff0000, v47
	v_lshlrev_b32_e32 v47, 16, v47
	v_add_f32_e32 v50, v57, v50
	v_pk_mul_f32 v[58:59], v[46:47], v[46:47]
	v_add_f32_e32 v50, v56, v50
	v_add_f32_e32 v50, v59, v50
	v_add_f32_e32 v50, v58, v50
	ds_bpermute_b32 v51, v180, v50
	s_waitcnt lgkmcnt(0)
	v_add_f32_e32 v50, v50, v51
	ds_bpermute_b32 v51, v181, v50
	s_waitcnt lgkmcnt(0)
	v_add_f32_e32 v50, v50, v51
	ds_bpermute_b32 v51, v182, v50
	s_waitcnt lgkmcnt(0)
	v_add_f32_e32 v50, v50, v51
	v_fmamk_f32 v50, v50, 0x3c800000, v197
	v_cmp_gt_f32_e32 vcc, s2, v50
	v_mul_f32_e32 v51, 0x4b800000, v50
	s_nop 0
	v_cndmask_b32_e32 v50, v50, v51, vcc
	v_rsq_f32_e32 v50, v50
	s_nop 0
	v_mul_f32_e32 v51, 0x45800000, v50
	v_cndmask_b32_e32 v50, v50, v51, vcc
	v_mul_f32_e32 v53, v40, v50
	v_mul_f32_e32 v45, v53, v45
	v_mul_f32_e32 v53, v36, v50
	v_mul_f32_e32 v51, v38, v50
	v_mul_f32_e32 v52, v39, v50
	v_mul_f32_e32 v47, v53, v47
	v_mul_f32_e32 v53, v41, v50
	v_mul_f32_e32 v48, v51, v48
	v_mul_f32_e32 v51, v34, v50
	v_mul_f32_e32 v49, v52, v49
	v_mul_f32_e32 v52, v35, v50
	v_mul_f32_e32 v53, v53, v44
	v_mul_f32_e32 v44, v37, v50
	v_mul_f32_e32 v51, v51, v55
	v_mul_f32_e32 v52, v52, v54
	v_mul_f32_e32 v50, v44, v46
	v_cvt_pk_bf16_f32 v44, v48, v49
	v_cvt_pk_bf16_f32 v45, v45, v53
	v_cvt_pk_bf16_f32 v46, v51, v52
	v_cvt_pk_bf16_f32 v47, v47, v50
	ds_write_b128 v107, v[44:47] offset:9216
	global_load_dwordx4 v[44:47], v[42:43], off offset:128
	s_waitcnt vmcnt(0)
	ds_write2_b64 v114, v[44:45], v[46:47] offset1:1
	v_mov_b64_e32 v[44:45], v[238:239]
	v_mov_b64_e32 v[46:47], v[240:241]
	v_lshlrev_b32_e32 v48, 16, v44
	v_and_b32_e32 v49, 0xffff0000, v44
	v_pk_mul_f32 v[50:51], v[48:49], v[48:49]
	v_and_b32_e32 v44, 0xffff0000, v45
	v_lshlrev_b32_e32 v45, 16, v45
	v_pk_mul_f32 v[52:53], v[44:45], v[44:45]
	v_add_f32_e32 v50, v50, v51
	v_and_b32_e32 v54, 0xffff0000, v46
	v_lshlrev_b32_e32 v55, 16, v46
	v_add_f32_e32 v50, v53, v50
	v_pk_mul_f32 v[56:57], v[54:55], v[54:55]
	v_add_f32_e32 v50, v52, v50
	v_and_b32_e32 v46, 0xffff0000, v47
	v_lshlrev_b32_e32 v47, 16, v47
	v_add_f32_e32 v50, v57, v50
	v_pk_mul_f32 v[58:59], v[46:47], v[46:47]
	v_add_f32_e32 v50, v56, v50
	v_add_f32_e32 v50, v59, v50
	v_add_f32_e32 v50, v58, v50
	ds_bpermute_b32 v51, v180, v50
	s_waitcnt lgkmcnt(0)
; #define LAS __attribute__((address_space(3)))
; __device__ __forceinline__ void attn_chunk(LAS unsigned char* Kl, LAS unsigned char* Vl, const bf16x8 (&qf)[4], f32x16 (&o)[2], float& m, float& l, int q, int half, int ii, int maskmode) {
;     f32x16 s[2];
; #pragma unroll
;     for (int kb = 0; kb < 2; ++kb) {
; #pragma unroll
;         for (int r = 0; r < 16; ++r) s[kb][r] = 0.f;
; #pragma unroll
;         for (int ks = 0; ks < 4; ++ks) { const bf16x8 kf = *(const LAS bf16x8*)(Kl + (32 * kb + q) * 144 + (2 * ks + half) * 16); s[kb] = __builtin_amdgcn_mfma_f32_32x32x16_bf16(kf, qf[ks], s[kb], 0, 0, 0); }
;     }
;     if (maskmode != 0) {
; #pragma unroll
;         for (int kb = 0; kb < 2; ++kb)
; #pragma unroll
;             for (int r = 0; r < 16; ++r) { const int jj = 32 * kb + 8 * (r >> 2) + 4 * half + (r & 3); const bool ok = (maskmode == 1) ? (jj >= ii) : (jj <= ii); if (!ok) s[kb][r] = -1e30f; }
;     }
;     float mx = s[0][0];
; #pragma unroll
;     for (int kb = 0; kb < 2; ++kb)
; #pragma unroll
;         for (int r = 0; r < 16; ++r) mx = fmaxf(mx, s[kb][r]);
;     mx = fmaxf(mx, __shfl_xor(mx, 32));
; __device__ __forceinline__ void attn_phase(const Params& P, LAS unsigned char* lds) {
;     ...
;         for (int ci = 0; ci < 4; ++ci) attn_stage(lds + ci * KSZ, lds + VBASE + ci * VSZ, qk, Vt, SEQ + 64 * ci, g, tid, P.k_gain, rope, false);
;         __syncthreads();
; #pragma unroll
;         for (int ci = 0; ci < 4; ++ci) attn_chunk(lds + ci * KSZ, lds + VBASE + ci * VSZ, qf, o, m, l, q, half, ii, 0);
	v_add_f32_e32 v50, v50, v51
	ds_bpermute_b32 v51, v181, v50
	s_waitcnt lgkmcnt(0)
	v_add_f32_e32 v50, v50, v51
	ds_bpermute_b32 v51, v182, v50
	s_waitcnt lgkmcnt(0)
	v_add_f32_e32 v50, v50, v51
	v_fmamk_f32 v50, v50, 0x3c800000, v197
	v_cmp_gt_f32_e32 vcc, s2, v50
	v_mul_f32_e32 v51, 0x4b800000, v50
	s_nop 0
	v_cndmask_b32_e32 v50, v50, v51, vcc
	v_rsq_f32_e32 v50, v50
	s_nop 0
	v_mul_f32_e32 v51, 0x45800000, v50
	v_cndmask_b32_e32 v50, v50, v51, vcc
	v_mul_f32_e32 v53, v40, v50
	v_mul_f32_e32 v45, v53, v45
	v_mul_f32_e32 v53, v36, v50
	v_mul_f32_e32 v51, v38, v50
	v_mul_f32_e32 v52, v39, v50
	v_mul_f32_e32 v47, v53, v47
	v_mul_f32_e32 v53, v41, v50
	v_mul_f32_e32 v48, v51, v48
	v_mul_f32_e32 v51, v34, v50
	v_mul_f32_e32 v49, v52, v49
	v_mul_f32_e32 v52, v35, v50
	v_mul_f32_e32 v53, v53, v44
	v_mul_f32_e32 v44, v37, v50
	v_mul_f32_e32 v51, v51, v55
	v_mul_f32_e32 v52, v52, v54
	v_mul_f32_e32 v50, v44, v46
	v_cvt_pk_bf16_f32 v44, v48, v49
	v_cvt_pk_bf16_f32 v45, v45, v53
	v_cvt_pk_bf16_f32 v46, v51, v52
	v_cvt_pk_bf16_f32 v47, v47, v50
	ds_write_b128 v107, v[44:47] offset:18432
	global_load_dwordx4 v[44:47], v[42:43], off offset:256
	s_waitcnt vmcnt(0)
	ds_write2_b64 v116, v[44:45], v[46:47] offset1:1
	v_mov_b64_e32 v[44:45], v[242:243]
	v_mov_b64_e32 v[46:47], v[244:245]
	v_lshlrev_b32_e32 v48, 16, v44
	v_and_b32_e32 v49, 0xffff0000, v44
	v_pk_mul_f32 v[50:51], v[48:49], v[48:49]
	v_and_b32_e32 v44, 0xffff0000, v45
	v_lshlrev_b32_e32 v45, 16, v45
	v_pk_mul_f32 v[52:53], v[44:45], v[44:45]
	v_add_f32_e32 v50, v50, v51
	v_and_b32_e32 v54, 0xffff0000, v46
	v_lshlrev_b32_e32 v55, 16, v46
	v_add_f32_e32 v50, v53, v50
	v_pk_mul_f32 v[56:57], v[54:55], v[54:55]
	v_add_f32_e32 v50, v52, v50
	v_and_b32_e32 v46, 0xffff0000, v47
	v_lshlrev_b32_e32 v47, 16, v47
	v_add_f32_e32 v50, v57, v50
	v_pk_mul_f32 v[58:59], v[46:47], v[46:47]
	v_add_f32_e32 v50, v56, v50
	v_add_f32_e32 v50, v59, v50
	v_add_f32_e32 v50, v58, v50
	ds_bpermute_b32 v51, v180, v50
	s_waitcnt lgkmcnt(0)
	v_add_f32_e32 v50, v50, v51
	ds_bpermute_b32 v51, v181, v50
	s_waitcnt lgkmcnt(0)
	v_add_f32_e32 v50, v50, v51
	ds_bpermute_b32 v51, v182, v50
	s_waitcnt lgkmcnt(0)
	v_add_f32_e32 v50, v50, v51
	v_fmamk_f32 v50, v50, 0x3c800000, v197
	v_cmp_gt_f32_e32 vcc, s2, v50
	v_mul_f32_e32 v51, 0x4b800000, v50
	s_nop 0
	v_cndmask_b32_e32 v50, v50, v51, vcc
	v_rsq_f32_e32 v50, v50
	s_nop 0
	v_mul_f32_e32 v51, 0x45800000, v50
	v_cndmask_b32_e32 v50, v50, v51, vcc
	v_mul_f32_e32 v38, v38, v50
	v_mul_f32_e32 v34, v34, v50
	v_mul_f32_e32 v35, v35, v50
	v_mul_f32_e32 v36, v36, v50
	v_mul_f32_e32 v38, v38, v48
	v_mul_f32_e32 v48, v34, v55
	v_mul_f32_e32 v34, v39, v50
	v_mul_f32_e32 v39, v35, v54
	v_mul_f32_e32 v35, v40, v50
	v_mul_f32_e32 v40, v36, v47
	v_mul_f32_e32 v36, v41, v50
	v_mul_f32_e32 v37, v37, v50
	v_mul_f32_e32 v34, v34, v49
	v_mul_f32_e32 v35, v35, v45
	v_mul_f32_e32 v36, v36, v44
	v_mul_f32_e32 v37, v37, v46
	v_cvt_pk_bf16_f32 v34, v38, v34
	v_cvt_pk_bf16_f32 v35, v35, v36
	v_cvt_pk_bf16_f32 v36, v48, v39
	v_cvt_pk_bf16_f32 v37, v40, v37
	ds_write_b128 v107, v[34:37] offset:27648
	global_load_dwordx4 v[34:37], v[42:43], off offset:384
	s_waitcnt vmcnt(0)
	ds_write2_b64 v115, v[34:35], v[36:37] offset1:1
	s_waitcnt lgkmcnt(0)
	s_barrier
	ds_read_b128 v[34:37], v91
	ds_read_b128 v[38:41], v91 offset:32
	s_waitcnt lgkmcnt(1)
	v_mfma_f32_32x32x16_bf16 v[50:65], v[34:37], v[78:81], 0
	ds_read_b128 v[34:37], v91 offset:64
	ds_read_b128 v[112:115], v91 offset:4640
	s_waitcnt lgkmcnt(2)
	v_mfma_f32_32x32x16_bf16 v[50:65], v[38:41], v[74:77], v[50:65]
	s_waitcnt lgkmcnt(1)
	v_mfma_f32_32x32x16_bf16 v[50:65], v[34:37], v[70:73], v[50:65]
	ds_read_b128 v[34:37], v91 offset:96
	s_waitcnt lgkmcnt(0)
	v_mfma_f32_32x32x16_bf16 v[50:65], v[34:37], v[66:69], v[50:65]
	ds_read_b128 v[34:37], v91 offset:4608
	s_waitcnt lgkmcnt(0)
	v_mfma_f32_32x32x16_bf16 v[34:49], v[34:37], v[78:81], 0
	s_nop 8
	v_max_f32_e32 v107, v51, v51
	v_mfma_f32_32x32x16_bf16 v[34:49], v[112:115], v[74:77], v[34:49]
	ds_read_b128 v[112:115], v91 offset:4672
	s_waitcnt lgkmcnt(0)
	v_mfma_f32_32x32x16_bf16 v[34:49], v[112:115], v[70:73], v[34:49]
	ds_read_b128 v[112:115], v91 offset:4704
	s_waitcnt lgkmcnt(0)
	v_mfma_f32_32x32x16_bf16 v[34:49], v[112:115], v[66:69], v[34:49]
	v_max_f32_e32 v112, v50, v50
	v_max_f32_e32 v107, v112, v107
	v_max3_f32 v107, v107, v52, v53
	v_max3_f32 v107, v107, v54, v55
	v_max3_f32 v107, v107, v56, v57
	v_max3_f32 v107, v107, v58, v59
	v_max3_f32 v107, v107, v60, v61
	v_max3_f32 v107, v107, v62, v63
	v_max3_f32 v107, v107, v64, v65
	s_nop 2
	v_max3_f32 v107, v107, v34, v35
	v_max3_f32 v107, v107, v36, v37
	v_max3_f32 v107, v107, v38, v39
	v_max3_f32 v107, v107, v40, v41
	v_max3_f32 v107, v107, v42, v43
	v_max3_f32 v107, v107, v44, v45
	v_max3_f32 v107, v107, v46, v47
	v_max3_f32 v107, v107, v48, v49
	ds_bpermute_b32 v112, v177, v107
	s_waitcnt lgkmcnt(0)
; #define LAS __attribute__((address_space(3)))
; __device__ __forceinline__ unsigned pk2(float lo, float hi) { unsigned r; asm("v_cvt_pk_bf16_f32 %0, %1, %2" : "=v"(r) : "v"(lo), "v"(hi)); return r; }
; __device__ __forceinline__ void attn_chunk(LAS unsigned char* Kl, LAS unsigned char* Vl, const bf16x8 (&qf)[4], f32x16 (&o)[2], float& m, float& l, int q, int half, int ii, int maskmode) {
;     ...
;     const float mn = fmaxf(m, mx), alpha = __expf(m - mn);
;     float ps = 0.f;
; #pragma unroll
;     for (int kb = 0; kb < 2; ++kb)
; #pragma unroll
;         for (int r = 0; r < 16; ++r) { const float p = __expf(s[kb][r] - mn); s[kb][r] = p; ps += p; }
;     l = l * alpha + ps; m = mn;
; #pragma unroll
;     for (int db = 0; db < 2; ++db)
; #pragma unroll
;         for (int r = 0; r < 16; ++r) o[db][r] *= alpha;
; #pragma unroll
;     for (int kb = 0; kb < 2; ++kb)
; #pragma unroll
;         for (int t = 0; t < 2; ++t) {
;             union { bf16x8 v; unsigned u[4]; } pf;
; #pragma unroll
;             for (int i = 0; i < 4; ++i) pf.u[i] = pk2(s[kb][8 * t + 2 * i], s[kb][8 * t + 2 * i + 1]);
; #pragma unroll
;             for (int db = 0; db < 2; ++db) {
;                 union { bf16x8 v; u32x2 h[2]; } vf;
;                 const LAS unsigned char* vp = Vl + (32 * db + q) * 136 + (32 * kb + 16 * t + 4 * half) * 2;
;                 vf.h[0] = *(const LAS u32x2*)vp; vf.h[1] = *(const LAS u32x2*)(vp + 16);
;                 o[db] = __builtin_amdgcn_mfma_f32_32x32x16_bf16(vf.v, pf.v, o[db], 0, 0, 0);
;             }
;         }
; }
	v_max3_f32 v113, v118, v107, v112
	v_sub_f32_e32 v34, v34, v113
	v_mul_f32_e32 v34, 0x3fb8aa3b, v34
	v_exp_f32_e32 v154, v34
	v_sub_f32_e32 v34, v35, v113
	v_mul_f32_e32 v34, 0x3fb8aa3b, v34
	v_exp_f32_e32 v156, v34
	v_sub_f32_e32 v34, v36, v113
	v_mul_f32_e32 v34, 0x3fb8aa3b, v34
	v_exp_f32_e32 v124, v34
	v_sub_f32_e32 v34, v37, v113
	v_mul_f32_e32 v34, 0x3fb8aa3b, v34
	v_exp_f32_e32 v126, v34
	v_sub_f32_e32 v34, v38, v113
	v_mul_f32_e32 v34, 0x3fb8aa3b, v34
	v_exp_f32_e32 v128, v34
	v_sub_f32_e32 v34, v39, v113
	v_mul_f32_e32 v34, 0x3fb8aa3b, v34
	v_exp_f32_e32 v130, v34
	v_sub_f32_e32 v34, v40, v113
	v_mul_f32_e32 v34, 0x3fb8aa3b, v34
	v_exp_f32_e32 v132, v34
	v_sub_f32_e32 v34, v41, v113
	v_sub_f32_e32 v50, v50, v113
	v_mul_f32_e32 v34, 0x3fb8aa3b, v34
	v_mul_f32_e32 v50, 0x3fb8aa3b, v50
	v_sub_f32_e32 v51, v51, v113
	v_exp_f32_e32 v134, v34
	v_sub_f32_e32 v34, v42, v113
	v_exp_f32_e32 v50, v50
	v_mul_f32_e32 v51, 0x3fb8aa3b, v51
	v_mul_f32_e32 v34, 0x3fb8aa3b, v34
	v_exp_f32_e32 v51, v51
	v_exp_f32_e32 v136, v34
	v_sub_f32_e32 v34, v43, v113
	v_mul_f32_e32 v34, 0x3fb8aa3b, v34
	v_exp_f32_e32 v138, v34
	v_sub_f32_e32 v34, v44, v113
	v_add_f32_e32 v112, 0, v50
	v_mul_f32_e32 v34, 0x3fb8aa3b, v34
	v_add_f32_e32 v174, v51, v112
	v_exp_f32_e32 v112, v34
	v_sub_f32_e32 v34, v45, v113
	v_mul_f32_e32 v34, 0x3fb8aa3b, v34
	v_exp_f32_e32 v114, v34
	v_sub_f32_e32 v34, v46, v113
	v_sub_f32_e32 v52, v52, v113
	v_mul_f32_e32 v34, 0x3fb8aa3b, v34
	v_mul_f32_e32 v52, 0x3fb8aa3b, v52
	v_exp_f32_e32 v116, v34
	v_sub_f32_e32 v34, v47, v113
	v_exp_f32_e32 v158, v52
	v_sub_f32_e32 v52, v53, v113
	v_mul_f32_e32 v34, 0x3fb8aa3b, v34
	v_sub_f32_e32 v107, v118, v113
	v_mul_f32_e32 v52, 0x3fb8aa3b, v52
	v_exp_f32_e32 v118, v34
	v_sub_f32_e32 v34, v48, v113
	v_exp_f32_e32 v160, v52
	v_sub_f32_e32 v52, v54, v113
	v_mul_f32_e32 v34, 0x3fb8aa3b, v34
	v_mul_f32_e32 v52, 0x3fb8aa3b, v52
	v_exp_f32_e32 v120, v34
	v_sub_f32_e32 v34, v49, v113
	v_mul_f32_e32 v107, 0x3fb8aa3b, v107
	v_exp_f32_e32 v162, v52
	v_sub_f32_e32 v52, v55, v113
	v_mul_f32_e32 v34, 0x3fb8aa3b, v34
	v_mul_f32_e32 v52, 0x3fb8aa3b, v52
	v_exp_f32_e32 v122, v34
	v_exp_f32_e32 v34, v107
	v_exp_f32_e32 v164, v52
	v_sub_f32_e32 v52, v56, v113
	ds_read2_b64 v[38:41], v119 offset0:128 offset1:130
	ds_read2_b64 v[42:45], v119 offset0:132 offset1:134
	v_mul_f32_e32 v52, 0x3fb8aa3b, v52
	v_exp_f32_e32 v166, v52
	v_sub_f32_e32 v52, v57, v113
	v_mul_f32_e32 v52, 0x3fb8aa3b, v52
	v_pk_mul_f32 v[18:19], v[18:19], v[34:35] op_sel_hi:[1,0]
	v_pk_mul_f32 v[20:21], v[20:21], v[34:35] op_sel_hi:[1,0]
	v_pk_mul_f32 v[22:23], v[22:23], v[34:35] op_sel_hi:[1,0]
	v_pk_mul_f32 v[24:25], v[24:25], v[34:35] op_sel_hi:[1,0]
	v_pk_mul_f32 v[26:27], v[26:27], v[34:35] op_sel_hi:[1,0]
	v_pk_mul_f32 v[28:29], v[28:29], v[34:35] op_sel_hi:[1,0]
	v_pk_mul_f32 v[30:31], v[30:31], v[34:35] op_sel_hi:[1,0]
	v_pk_mul_f32 v[32:33], v[32:33], v[34:35] op_sel_hi:[1,0]
	v_exp_f32_e32 v168, v52
	v_mul_f32_e32 v140, v121, v34
	v_pk_mul_f32 v[2:3], v[2:3], v[34:35] op_sel_hi:[1,0]
	v_pk_mul_f32 v[4:5], v[4:5], v[34:35] op_sel_hi:[1,0]
	v_pk_mul_f32 v[6:7], v[6:7], v[34:35] op_sel_hi:[1,0]
	v_pk_mul_f32 v[8:9], v[8:9], v[34:35] op_sel_hi:[1,0]
	v_pk_mul_f32 v[10:11], v[10:11], v[34:35] op_sel_hi:[1,0]
	v_pk_mul_f32 v[12:13], v[12:13], v[34:35] op_sel_hi:[1,0]
	v_pk_mul_f32 v[14:15], v[14:15], v[34:35] op_sel_hi:[1,0]
	v_pk_mul_f32 v[16:17], v[16:17], v[34:35] op_sel_hi:[1,0]
	v_cvt_pk_bf16_f32 v34, v50, v51
	v_cvt_pk_bf16_f32 v35, v158, v160
	v_cvt_pk_bf16_f32 v36, v162, v164
	v_cvt_pk_bf16_f32 v37, v166, v168
	v_sub_f32_e32 v52, v58, v113
	s_waitcnt lgkmcnt(1)
	v_mfma_f32_32x32x16_bf16 v[18:33], v[38:41], v[34:37], v[18:33]
	ds_read2_b64 v[38:41], v117 offset0:160 offset1:162
	v_mul_f32_e32 v52, 0x3fb8aa3b, v52
	v_exp_f32_e32 v170, v52
	v_sub_f32_e32 v52, v59, v113
	v_mul_f32_e32 v52, 0x3fb8aa3b, v52
	v_exp_f32_e32 v172, v52
	v_sub_f32_e32 v52, v60, v113
	v_mul_f32_e32 v52, 0x3fb8aa3b, v52
	v_exp_f32_e32 v142, v52
	v_sub_f32_e32 v52, v61, v113
	v_mul_f32_e32 v52, 0x3fb8aa3b, v52
	s_waitcnt lgkmcnt(0)
	v_mfma_f32_32x32x16_bf16 v[2:17], v[38:41], v[34:37], v[2:17]
	ds_read2_b64 v[38:41], v117 offset0:164 offset1:166
	v_exp_f32_e32 v144, v52
	v_sub_f32_e32 v52, v62, v113
	v_mul_f32_e32 v52, 0x3fb8aa3b, v52
	v_exp_f32_e32 v146, v52
	v_sub_f32_e32 v52, v63, v113
	v_mul_f32_e32 v52, 0x3fb8aa3b, v52
	v_exp_f32_e32 v148, v52
	v_sub_f32_e32 v52, v64, v113
	v_mul_f32_e32 v52, 0x3fb8aa3b, v52
	v_exp_f32_e32 v150, v52
	v_sub_f32_e32 v52, v65, v113
	v_mul_f32_e32 v52, 0x3fb8aa3b, v52
	v_exp_f32_e32 v152, v52
	v_cvt_pk_bf16_f32 v34, v170, v172
	v_cvt_pk_bf16_f32 v35, v142, v144
	v_cvt_pk_bf16_f32 v36, v146, v148
	v_cvt_pk_bf16_f32 v37, v150, v152
	ds_read_b128 v[218:221], v91 offset:13856
	s_waitcnt lgkmcnt(1)
	v_mfma_f32_32x32x16_bf16 v[2:17], v[38:41], v[34:37], v[2:17]
	ds_read2_b64 v[38:41], v119 offset0:136 offset1:138
	v_mfma_f32_32x32x16_bf16 v[18:33], v[42:45], v[34:37], v[18:33]
	v_cvt_pk_bf16_f32 v34, v154, v156
	v_cvt_pk_bf16_f32 v35, v124, v126
	v_cvt_pk_bf16_f32 v36, v128, v130
	v_cvt_pk_bf16_f32 v37, v132, v134
	s_waitcnt lgkmcnt(0)
	v_mfma_f32_32x32x16_bf16 v[18:33], v[38:41], v[34:37], v[18:33]
	ds_read2_b64 v[38:41], v117 offset0:168 offset1:170
	s_waitcnt lgkmcnt(0)
	v_mfma_f32_32x32x16_bf16 v[2:17], v[38:41], v[34:37], v[2:17]
	ds_read2_b64 v[38:41], v119 offset0:140 offset1:142
	v_cvt_pk_bf16_f32 v34, v136, v138
	v_cvt_pk_bf16_f32 v35, v112, v114
	v_cvt_pk_bf16_f32 v36, v116, v118
	v_cvt_pk_bf16_f32 v37, v120, v122
	s_waitcnt lgkmcnt(0)
	v_mfma_f32_32x32x16_bf16 v[18:33], v[38:41], v[34:37], v[18:33]
	ds_read2_b64 v[38:41], v117 offset0:172 offset1:174
	s_waitcnt lgkmcnt(0)
; #define LAS __attribute__((address_space(3)))
; __device__ __forceinline__ void attn_chunk(LAS unsigned char* Kl, LAS unsigned char* Vl, const bf16x8 (&qf)[4], f32x16 (&o)[2], float& m, float& l, int q, int half, int ii, int maskmode) {
;     ...
;     for (int kb = 0; kb < 2; ++kb) {
; #pragma unroll
;         for (int r = 0; r < 16; ++r) s[kb][r] = 0.f;
; #pragma unroll
;         for (int ks = 0; ks < 4; ++ks) { const bf16x8 kf = *(const LAS bf16x8*)(Kl + (32 * kb + q) * 144 + (2 * ks + half) * 16); s[kb] = __builtin_amdgcn_mfma_f32_32x32x16_bf16(kf, qf[ks], s[kb], 0, 0, 0); }
;     }
;     if (maskmode != 0) {
; #pragma unroll
;         for (int kb = 0; kb < 2; ++kb)
; #pragma unroll
;             for (int r = 0; r < 16; ++r) { const int jj = 32 * kb + 8 * (r >> 2) + 4 * half + (r & 3); const bool ok = (maskmode == 1) ? (jj >= ii) : (jj <= ii); if (!ok) s[kb][r] = -1e30f; }
;     }
;     float mx = s[0][0];
; #pragma unroll
;     for (int kb = 0; kb < 2; ++kb)
; #pragma unroll
;         for (int r = 0; r < 16; ++r) mx = fmaxf(mx, s[kb][r]);
;     mx = fmaxf(mx, __shfl_xor(mx, 32));
;     const float mn = fmaxf(m, mx), alpha = __expf(m - mn);
;     float ps = 0.f;
; #pragma unroll
;     for (int kb = 0; kb < 2; ++kb)
; #pragma unroll
;         for (int r = 0; r < 16; ++r) { const float p = __expf(s[kb][r] - mn); s[kb][r] = p; ps += p; }
;     l = l * alpha + ps; m = mn;
	v_mfma_f32_32x32x16_bf16 v[2:17], v[38:41], v[34:37], v[2:17]
	ds_read_b128 v[34:37], v91 offset:9216
	s_waitcnt lgkmcnt(0)
	v_mfma_f32_32x32x16_bf16 v[50:65], v[34:37], v[78:81], 0
	ds_read_b128 v[34:37], v91 offset:9248
	s_waitcnt lgkmcnt(0)
	v_mfma_f32_32x32x16_bf16 v[50:65], v[34:37], v[74:77], v[50:65]
	ds_read_b128 v[34:37], v91 offset:9280
	s_waitcnt lgkmcnt(0)
	v_mfma_f32_32x32x16_bf16 v[50:65], v[34:37], v[70:73], v[50:65]
	ds_read_b128 v[34:37], v91 offset:9312
	s_waitcnt lgkmcnt(0)
	v_mfma_f32_32x32x16_bf16 v[50:65], v[34:37], v[66:69], v[50:65]
	ds_read_b128 v[34:37], v91 offset:13824
	s_waitcnt lgkmcnt(0)
	v_mfma_f32_32x32x16_bf16 v[34:49], v[34:37], v[78:81], 0
	s_nop 8
	v_max_f32_e32 v107, v51, v51
	v_max_f32_e32 v115, v50, v50
	v_max_f32_e32 v107, v115, v107
	v_max3_f32 v107, v107, v52, v53
	v_max3_f32 v107, v107, v54, v55
	v_max3_f32 v107, v107, v56, v57
	v_max3_f32 v107, v107, v58, v59
	v_mfma_f32_32x32x16_bf16 v[34:49], v[218:221], v[74:77], v[34:49]
	ds_read_b128 v[218:221], v91 offset:13888
	v_max3_f32 v107, v107, v60, v61
	v_max3_f32 v107, v107, v62, v63
	v_max3_f32 v107, v107, v64, v65
	s_waitcnt lgkmcnt(0)
	v_mfma_f32_32x32x16_bf16 v[34:49], v[218:221], v[70:73], v[34:49]
	ds_read_b128 v[218:221], v91 offset:13920
	s_waitcnt lgkmcnt(0)
	v_mfma_f32_32x32x16_bf16 v[34:49], v[218:221], v[66:69], v[34:49]
	s_nop 11
	v_max3_f32 v107, v107, v34, v35
	v_max3_f32 v107, v107, v36, v37
	v_max3_f32 v107, v107, v38, v39
	v_max3_f32 v107, v107, v40, v41
	v_max3_f32 v107, v107, v42, v43
	v_max3_f32 v107, v107, v44, v45
	v_max3_f32 v107, v107, v46, v47
	v_max3_f32 v107, v107, v48, v49
	ds_bpermute_b32 v115, v177, v107
	s_waitcnt lgkmcnt(0)
	v_max3_f32 v107, v113, v107, v115
	v_sub_f32_e32 v50, v50, v107
	v_mul_f32_e32 v50, 0x3fb8aa3b, v50
	v_exp_f32_e32 v159, v50
	v_sub_f32_e32 v50, v51, v107
	v_mul_f32_e32 v50, 0x3fb8aa3b, v50
	v_exp_f32_e32 v161, v50
	v_sub_f32_e32 v50, v52, v107
	v_mul_f32_e32 v50, 0x3fb8aa3b, v50
	v_exp_f32_e32 v163, v50
	v_sub_f32_e32 v50, v53, v107
	v_mul_f32_e32 v50, 0x3fb8aa3b, v50
	v_exp_f32_e32 v165, v50
	v_sub_f32_e32 v50, v54, v107
	v_mul_f32_e32 v50, 0x3fb8aa3b, v50
	v_exp_f32_e32 v167, v50
	v_sub_f32_e32 v50, v55, v107
	v_mul_f32_e32 v50, 0x3fb8aa3b, v50
	v_exp_f32_e32 v169, v50
	v_sub_f32_e32 v50, v56, v107
	v_mul_f32_e32 v50, 0x3fb8aa3b, v50
	v_exp_f32_e32 v171, v50
	v_sub_f32_e32 v50, v57, v107
	v_mul_f32_e32 v50, 0x3fb8aa3b, v50
	v_sub_f32_e32 v52, v59, v107
	v_exp_f32_e32 v173, v50
	v_sub_f32_e32 v50, v58, v107
	v_mul_f32_e32 v52, 0x3fb8aa3b, v52
	v_mul_f32_e32 v50, 0x3fb8aa3b, v50
	v_exp_f32_e32 v145, v52
	v_sub_f32_e32 v52, v60, v107
	v_sub_f32_e32 v34, v34, v107
	v_exp_f32_e32 v143, v50
	v_pk_add_f32 v[50:51], v[158:159], v[174:175]
	v_mul_f32_e32 v52, 0x3fb8aa3b, v52
	v_mul_f32_e32 v34, 0x3fb8aa3b, v34
	v_pk_add_f32 v[50:51], v[160:161], v[50:51]
	v_exp_f32_e32 v147, v52
	v_sub_f32_e32 v52, v61, v107
	v_exp_f32_e32 v125, v34
	v_sub_f32_e32 v34, v35, v107
	v_pk_add_f32 v[50:51], v[162:163], v[50:51]
	v_mul_f32_e32 v52, 0x3fb8aa3b, v52
	v_mul_f32_e32 v34, 0x3fb8aa3b, v34
	v_pk_add_f32 v[50:51], v[164:165], v[50:51]
	v_exp_f32_e32 v149, v52
	v_sub_f32_e32 v52, v62, v107
	v_exp_f32_e32 v127, v34
	v_sub_f32_e32 v34, v36, v107
	v_sub_f32_e32 v36, v38, v107
	v_pk_add_f32 v[50:51], v[166:167], v[50:51]
	v_mul_f32_e32 v52, 0x3fb8aa3b, v52
	v_mul_f32_e32 v36, 0x3fb8aa3b, v36
	v_pk_add_f32 v[50:51], v[168:169], v[50:51]
	v_exp_f32_e32 v151, v52
	v_sub_f32_e32 v52, v63, v107
	v_exp_f32_e32 v133, v36
	v_sub_f32_e32 v36, v39, v107
	v_pk_add_f32 v[50:51], v[170:171], v[50:51]
	v_mul_f32_e32 v52, 0x3fb8aa3b, v52
	v_mul_f32_e32 v34, 0x3fb8aa3b, v34
	v_mul_f32_e32 v36, 0x3fb8aa3b, v36
	v_pk_add_f32 v[50:51], v[172:173], v[50:51]
	v_exp_f32_e32 v153, v52
	v_sub_f32_e32 v52, v64, v107
	v_exp_f32_e32 v129, v34
	v_sub_f32_e32 v34, v37, v107
	v_exp_f32_e32 v135, v36
	v_sub_f32_e32 v36, v40, v107
	v_pk_add_f32 v[50:51], v[142:143], v[50:51]
	v_mul_f32_e32 v52, 0x3fb8aa3b, v52
	v_mul_f32_e32 v34, 0x3fb8aa3b, v34
	v_mul_f32_e32 v36, 0x3fb8aa3b, v36
	v_exp_f32_e32 v155, v52
	v_sub_f32_e32 v52, v65, v107
	v_exp_f32_e32 v131, v34
	v_pk_add_f32 v[34:35], v[144:145], v[50:51]
	v_exp_f32_e32 v137, v36
	v_sub_f32_e32 v36, v41, v107
	v_mul_f32_e32 v52, 0x3fb8aa3b, v52
	v_pk_add_f32 v[34:35], v[146:147], v[34:35]
	v_mul_f32_e32 v36, 0x3fb8aa3b, v36
	v_exp_f32_e32 v157, v52
	v_pk_add_f32 v[34:35], v[148:149], v[34:35]
	v_exp_f32_e32 v139, v36
	v_sub_f32_e32 v36, v42, v107
	v_sub_f32_e32 v113, v113, v107
	v_pk_add_f32 v[34:35], v[150:151], v[34:35]
	v_mul_f32_e32 v36, 0x3fb8aa3b, v36
	v_mul_f32_e32 v214, 0x3fb8aa3b, v113
	v_pk_add_f32 v[34:35], v[152:153], v[34:35]
	v_exp_f32_e32 v113, v36
	v_sub_f32_e32 v36, v43, v107
	v_pk_add_f32 v[34:35], v[154:155], v[34:35]
	v_mul_f32_e32 v36, 0x3fb8aa3b, v36
	v_pk_add_f32 v[34:35], v[156:157], v[34:35]
	v_exp_f32_e32 v115, v36
	v_sub_f32_e32 v36, v44, v107
	v_pk_add_f32 v[34:35], v[124:125], v[34:35]
	v_mul_f32_e32 v36, 0x3fb8aa3b, v36
	v_pk_add_f32 v[34:35], v[126:127], v[34:35]
	v_exp_f32_e32 v117, v36
	v_sub_f32_e32 v36, v45, v107
	v_pk_add_f32 v[34:35], v[128:129], v[34:35]
	v_mul_f32_e32 v36, 0x3fb8aa3b, v36
	v_pk_add_f32 v[34:35], v[130:131], v[34:35]
	v_exp_f32_e32 v119, v36
	v_sub_f32_e32 v36, v46, v107
	v_mul_f32_e32 v36, 0x3fb8aa3b, v36
	v_exp_f32_e32 v52, v214
	v_pk_add_f32 v[34:35], v[132:133], v[34:35]
	v_exp_f32_e32 v121, v36
	v_sub_f32_e32 v36, v47, v107
	v_pk_add_f32 v[34:35], v[134:135], v[34:35]
	v_mul_f32_e32 v36, 0x3fb8aa3b, v36
	v_pk_add_f32 v[34:35], v[136:137], v[34:35]
	v_exp_f32_e32 v123, v36
	v_sub_f32_e32 v36, v48, v107
	v_pk_add_f32 v[34:35], v[138:139], v[34:35]
; #define LAS __attribute__((address_space(3)))
; __device__ __forceinline__ unsigned pk2(float lo, float hi) { unsigned r; asm("v_cvt_pk_bf16_f32 %0, %1, %2" : "=v"(r) : "v"(lo), "v"(hi)); return r; }
; __device__ __forceinline__ void attn_chunk(LAS unsigned char* Kl, LAS unsigned char* Vl, const bf16x8 (&qf)[4], f32x16 (&o)[2], float& m, float& l, int q, int half, int ii, int maskmode) {
;     ...
;     for (int kb = 0; kb < 2; ++kb) {
; #pragma unroll
;         for (int r = 0; r < 16; ++r) s[kb][r] = 0.f;
; #pragma unroll
;         for (int ks = 0; ks < 4; ++ks) { const bf16x8 kf = *(const LAS bf16x8*)(Kl + (32 * kb + q) * 144 + (2 * ks + half) * 16); s[kb] = __builtin_amdgcn_mfma_f32_32x32x16_bf16(kf, qf[ks], s[kb], 0, 0, 0); }
;     }
;     if (maskmode != 0) {
; #pragma unroll
;         for (int kb = 0; kb < 2; ++kb)
; #pragma unroll
;             for (int r = 0; r < 16; ++r) { const int jj = 32 * kb + 8 * (r >> 2) + 4 * half + (r & 3); const bool ok = (maskmode == 1) ? (jj >= ii) : (jj <= ii); if (!ok) s[kb][r] = -1e30f; }
;     }
;     float mx = s[0][0];
; #pragma unroll
;     for (int kb = 0; kb < 2; ++kb)
; #pragma unroll
;         for (int r = 0; r < 16; ++r) mx = fmaxf(mx, s[kb][r]);
;     mx = fmaxf(mx, __shfl_xor(mx, 32));
;     ...
; #pragma unroll
;     for (int db = 0; db < 2; ++db)
; #pragma unroll
;         for (int r = 0; r < 16; ++r) o[db][r] *= alpha;
; #pragma unroll
;     for (int kb = 0; kb < 2; ++kb)
; #pragma unroll
;         for (int t = 0; t < 2; ++t) {
;             union { bf16x8 v; unsigned u[4]; } pf;
; #pragma unroll
;             for (int i = 0; i < 4; ++i) pf.u[i] = pk2(s[kb][8 * t + 2 * i], s[kb][8 * t + 2 * i + 1]);
; #pragma unroll
;             for (int db = 0; db < 2; ++db) {
;                 union { bf16x8 v; u32x2 h[2]; } vf;
;                 const LAS unsigned char* vp = Vl + (32 * db + q) * 136 + (32 * kb + 16 * t + 4 * half) * 2;
;                 vf.h[0] = *(const LAS u32x2*)vp; vf.h[1] = *(const LAS u32x2*)(vp + 16);
;                 o[db] = __builtin_amdgcn_mfma_f32_32x32x16_bf16(vf.v, pf.v, o[db], 0, 0, 0);
;             }
;         }
; }
	v_mul_f32_e32 v36, 0x3fb8aa3b, v36
	v_pk_add_f32 v[34:35], v[112:113], v[34:35]
	v_pk_mul_f32 v[40:41], v[24:25], v[52:53] op_sel_hi:[1,0]
	v_pk_mul_f32 v[38:39], v[22:23], v[52:53] op_sel_hi:[1,0]
	v_pk_mul_f32 v[24:25], v[8:9], v[52:53] op_sel_hi:[1,0]
	v_pk_mul_f32 v[22:23], v[6:7], v[52:53] op_sel_hi:[1,0]
	ds_read2_b64 v[6:9], v192 offset0:192 offset1:194
	v_exp_f32_e32 v141, v36
	v_sub_f32_e32 v36, v49, v107
	v_pk_add_f32 v[34:35], v[114:115], v[34:35]
	v_mul_f32_e32 v36, 0x3fb8aa3b, v36
	v_pk_add_f32 v[34:35], v[116:117], v[34:35]
	v_exp_f32_e32 v50, v36
	v_pk_add_f32 v[34:35], v[118:119], v[34:35]
	v_pk_mul_f32 v[48:49], v[32:33], v[52:53] op_sel_hi:[1,0]
	v_pk_add_f32 v[34:35], v[120:121], v[34:35]
	v_pk_mul_f32 v[46:47], v[30:31], v[52:53] op_sel_hi:[1,0]
	v_pk_add_f32 v[34:35], v[122:123], v[34:35]
	v_pk_mul_f32 v[44:45], v[28:29], v[52:53] op_sel_hi:[1,0]
	v_pk_add_f32 v[34:35], v[140:141], v[34:35]
	v_pk_mul_f32 v[42:43], v[26:27], v[52:53] op_sel_hi:[1,0]
	v_add_f32_e32 v156, v35, v50
	v_fmac_f32_e32 v156, v34, v52
	v_pk_mul_f32 v[36:37], v[20:21], v[52:53] op_sel_hi:[1,0]
	v_pk_mul_f32 v[34:35], v[18:19], v[52:53] op_sel_hi:[1,0]
	v_pk_mul_f32 v[20:21], v[4:5], v[52:53] op_sel_hi:[1,0]
	v_pk_mul_f32 v[18:19], v[2:3], v[52:53] op_sel_hi:[1,0]
	v_cvt_pk_bf16_f32 v2, v159, v161
	v_cvt_pk_bf16_f32 v3, v163, v165
	v_cvt_pk_bf16_f32 v4, v167, v169
	v_cvt_pk_bf16_f32 v5, v171, v173
	v_pk_mul_f32 v[32:33], v[16:17], v[52:53] op_sel_hi:[1,0]
	s_waitcnt lgkmcnt(0)
	v_mfma_f32_32x32x16_bf16 v[34:49], v[6:9], v[2:5], v[34:49]
	ds_read2_b64 v[6:9], v191 offset0:224 offset1:226
	v_mul_f32_e64 v30, v14, v52
	v_mul_f32_e64 v31, v15, v52
	v_mul_f32_e64 v28, v12, v52
	v_mul_f32_e64 v29, v13, v52
	v_pk_mul_f32 v[26:27], v[10:11], v[52:53] op_sel_hi:[1,0]
	s_waitcnt lgkmcnt(0)
	s_nop 0
	v_mfma_f32_32x32x16_bf16 v[18:33], v[6:9], v[2:5], v[18:33]
	ds_read2_b64 v[6:9], v192 offset0:196 offset1:198
	v_cvt_pk_bf16_f32 v2, v143, v145
	v_cvt_pk_bf16_f32 v3, v147, v149
	v_cvt_pk_bf16_f32 v4, v151, v153
	v_cvt_pk_bf16_f32 v5, v155, v157
	s_waitcnt lgkmcnt(0)
	v_mfma_f32_32x32x16_bf16 v[34:49], v[6:9], v[2:5], v[34:49]
	ds_read2_b64 v[6:9], v191 offset0:228 offset1:230
	s_waitcnt lgkmcnt(0)
	v_mfma_f32_32x32x16_bf16 v[18:33], v[6:9], v[2:5], v[18:33]
	ds_read2_b64 v[6:9], v192 offset0:200 offset1:202
	v_cvt_pk_bf16_f32 v2, v125, v127
	v_cvt_pk_bf16_f32 v3, v129, v131
	v_cvt_pk_bf16_f32 v4, v133, v135
	v_cvt_pk_bf16_f32 v5, v137, v139
	s_waitcnt lgkmcnt(0)
	v_mfma_f32_32x32x16_bf16 v[34:49], v[6:9], v[2:5], v[34:49]
	ds_read2_b64 v[6:9], v191 offset0:232 offset1:234
	s_waitcnt lgkmcnt(0)
	v_mfma_f32_32x32x16_bf16 v[18:33], v[6:9], v[2:5], v[18:33]
	ds_read2_b64 v[6:9], v192 offset0:204 offset1:206
	v_cvt_pk_bf16_f32 v2, v113, v115
	v_cvt_pk_bf16_f32 v3, v117, v119
	v_cvt_pk_bf16_f32 v4, v121, v123
	v_cvt_pk_bf16_f32 v5, v141, v50
	ds_read_b128 v[112:115], v91 offset:23072
	s_waitcnt lgkmcnt(1)
	v_mfma_f32_32x32x16_bf16 v[34:49], v[6:9], v[2:5], v[34:49]
	ds_read2_b64 v[6:9], v191 offset0:236 offset1:238
	s_waitcnt lgkmcnt(0)
	v_mfma_f32_32x32x16_bf16 v[18:33], v[6:9], v[2:5], v[18:33]
	ds_read_b128 v[2:5], v91 offset:18432
	s_waitcnt lgkmcnt(0)
	v_mfma_f32_32x32x16_bf16 v[50:65], v[2:5], v[78:81], 0
	ds_read_b128 v[2:5], v91 offset:18464
	s_waitcnt lgkmcnt(0)
	v_mfma_f32_32x32x16_bf16 v[50:65], v[2:5], v[74:77], v[50:65]
	ds_read_b128 v[2:5], v91 offset:18496
	s_waitcnt lgkmcnt(0)
	v_mfma_f32_32x32x16_bf16 v[50:65], v[2:5], v[70:73], v[50:65]
	ds_read_b128 v[2:5], v91 offset:18528
	s_waitcnt lgkmcnt(0)
	v_mfma_f32_32x32x16_bf16 v[50:65], v[2:5], v[66:69], v[50:65]
	ds_read_b128 v[2:5], v91 offset:23040
	s_waitcnt lgkmcnt(0)
	v_mfma_f32_32x32x16_bf16 v[2:17], v[2:5], v[78:81], 0
	v_mfma_f32_32x32x16_bf16 v[2:17], v[112:115], v[74:77], v[2:17]
	ds_read_b128 v[112:115], v91 offset:23104
	s_waitcnt lgkmcnt(0)
	v_mfma_f32_32x32x16_bf16 v[2:17], v[112:115], v[70:73], v[2:17]
	ds_read_b128 v[112:115], v91 offset:23136
	s_waitcnt lgkmcnt(0)
	v_mfma_f32_32x32x16_bf16 v[2:17], v[112:115], v[66:69], v[2:17]
	s_nop 1
	v_max_f32_e32 v112, v51, v51
	v_max_f32_e32 v113, v50, v50
	v_max_f32_e32 v112, v113, v112
	v_max3_f32 v112, v112, v52, v53
	v_max3_f32 v112, v112, v54, v55
	v_max3_f32 v112, v112, v56, v57
	v_max3_f32 v112, v112, v58, v59
	v_max3_f32 v112, v112, v60, v61
	v_max3_f32 v112, v112, v62, v63
	v_max3_f32 v112, v112, v64, v65
	v_max3_f32 v112, v112, v2, v3
	v_max3_f32 v112, v112, v4, v5
	v_max3_f32 v112, v112, v6, v7
	v_max3_f32 v112, v112, v8, v9
	v_max3_f32 v112, v112, v10, v11
	v_max3_f32 v112, v112, v12, v13
	v_max3_f32 v112, v112, v14, v15
	v_max3_f32 v112, v112, v16, v17
	ds_bpermute_b32 v113, v177, v112
	s_waitcnt lgkmcnt(0)
; #define LAS __attribute__((address_space(3)))
; __device__ __forceinline__ unsigned pk2(float lo, float hi) { unsigned r; asm("v_cvt_pk_bf16_f32 %0, %1, %2" : "=v"(r) : "v"(lo), "v"(hi)); return r; }
; __device__ __forceinline__ void attn_chunk(LAS unsigned char* Kl, LAS unsigned char* Vl, const bf16x8 (&qf)[4], f32x16 (&o)[2], float& m, float& l, int q, int half, int ii, int maskmode) {
;     ...
;     const float mn = fmaxf(m, mx), alpha = __expf(m - mn);
;     float ps = 0.f;
; #pragma unroll
;     for (int kb = 0; kb < 2; ++kb)
; #pragma unroll
;         for (int r = 0; r < 16; ++r) { const float p = __expf(s[kb][r] - mn); s[kb][r] = p; ps += p; }
;     l = l * alpha + ps; m = mn;
; #pragma unroll
;     for (int db = 0; db < 2; ++db)
; #pragma unroll
;         for (int r = 0; r < 16; ++r) o[db][r] *= alpha;
; #pragma unroll
;     for (int kb = 0; kb < 2; ++kb)
; #pragma unroll
;         for (int t = 0; t < 2; ++t) {
;             union { bf16x8 v; unsigned u[4]; } pf;
; #pragma unroll
;             for (int i = 0; i < 4; ++i) pf.u[i] = pk2(s[kb][8 * t + 2 * i], s[kb][8 * t + 2 * i + 1]);
; #pragma unroll
;             for (int db = 0; db < 2; ++db) {
;                 union { bf16x8 v; u32x2 h[2]; } vf;
;                 const LAS unsigned char* vp = Vl + (32 * db + q) * 136 + (32 * kb + 16 * t + 4 * half) * 2;
;                 vf.h[0] = *(const LAS u32x2*)vp; vf.h[1] = *(const LAS u32x2*)(vp + 16);
;                 o[db] = __builtin_amdgcn_mfma_f32_32x32x16_bf16(vf.v, pf.v, o[db], 0, 0, 0);
;             }
;         }
; }
	v_max3_f32 v113, v107, v112, v113
	v_sub_f32_e32 v50, v50, v113
	v_mul_f32_e32 v50, 0x3fb8aa3b, v50
	v_sub_f32_e32 v51, v51, v113
	v_exp_f32_e32 v115, v50
	v_mul_f32_e32 v51, 0x3fb8aa3b, v51
	v_exp_f32_e32 v51, v51
	v_sub_f32_e32 v2, v2, v113
	v_add_f32_e32 v50, 0, v115
	v_mul_f32_e32 v2, 0x3fb8aa3b, v2
	v_add_f32_e32 v174, v51, v50
	v_sub_f32_e32 v50, v52, v113
	v_mul_f32_e32 v50, 0x3fb8aa3b, v50
	v_exp_f32_e32 v158, v50
	v_sub_f32_e32 v50, v53, v113
	v_mul_f32_e32 v50, 0x3fb8aa3b, v50
	v_exp_f32_e32 v160, v50
	v_sub_f32_e32 v50, v54, v113
	v_mul_f32_e32 v50, 0x3fb8aa3b, v50
	v_exp_f32_e32 v162, v50
	v_sub_f32_e32 v50, v55, v113
	v_mul_f32_e32 v50, 0x3fb8aa3b, v50
	v_exp_f32_e32 v164, v50
	v_sub_f32_e32 v50, v56, v113
	v_mul_f32_e32 v50, 0x3fb8aa3b, v50
	v_exp_f32_e32 v166, v50
	v_sub_f32_e32 v50, v57, v113
	v_exp_f32_e32 v146, v2
	v_sub_f32_e32 v2, v3, v113
	v_mul_f32_e32 v50, 0x3fb8aa3b, v50
	v_mul_f32_e32 v2, 0x3fb8aa3b, v2
	v_exp_f32_e32 v168, v50
	v_sub_f32_e32 v50, v58, v113
	v_exp_f32_e32 v150, v2
	v_sub_f32_e32 v2, v4, v113
	v_mul_f32_e32 v50, 0x3fb8aa3b, v50
	v_mul_f32_e32 v2, 0x3fb8aa3b, v2
	v_exp_f32_e32 v170, v50
	v_sub_f32_e32 v50, v59, v113
	v_exp_f32_e32 v128, v2
	v_sub_f32_e32 v2, v5, v113
	v_mul_f32_e32 v50, 0x3fb8aa3b, v50
	v_mul_f32_e32 v2, 0x3fb8aa3b, v2
	v_exp_f32_e32 v172, v50
	v_sub_f32_e32 v50, v60, v113
	v_exp_f32_e32 v132, v2
	v_sub_f32_e32 v2, v6, v113
	v_mul_f32_e32 v50, 0x3fb8aa3b, v50
	v_mul_f32_e32 v2, 0x3fb8aa3b, v2
	v_exp_f32_e32 v124, v50
	v_sub_f32_e32 v50, v61, v113
	v_exp_f32_e32 v136, v2
	v_sub_f32_e32 v2, v7, v113
	v_mul_f32_e32 v50, 0x3fb8aa3b, v50
	v_mul_f32_e32 v2, 0x3fb8aa3b, v2
	v_exp_f32_e32 v126, v50
	v_sub_f32_e32 v50, v62, v113
	v_exp_f32_e32 v140, v2
	v_sub_f32_e32 v2, v8, v113
	v_mul_f32_e32 v50, 0x3fb8aa3b, v50
	v_mul_f32_e32 v2, 0x3fb8aa3b, v2
	v_exp_f32_e32 v130, v50
	v_sub_f32_e32 v50, v63, v113
	v_exp_f32_e32 v144, v2
	v_sub_f32_e32 v2, v9, v113
	v_mul_f32_e32 v50, 0x3fb8aa3b, v50
	v_mul_f32_e32 v2, 0x3fb8aa3b, v2
	v_exp_f32_e32 v134, v50
	v_sub_f32_e32 v50, v64, v113
	v_exp_f32_e32 v148, v2
	v_sub_f32_e32 v2, v10, v113
	v_mul_f32_e32 v50, 0x3fb8aa3b, v50
	v_mul_f32_e32 v2, 0x3fb8aa3b, v2
	v_sub_f32_e32 v107, v107, v113
	v_exp_f32_e32 v138, v50
	v_sub_f32_e32 v50, v65, v113
	v_exp_f32_e32 v152, v2
	v_sub_f32_e32 v2, v11, v113
	v_mul_f32_e32 v107, 0x3fb8aa3b, v107
	v_mul_f32_e32 v50, 0x3fb8aa3b, v50
	v_mul_f32_e32 v2, 0x3fb8aa3b, v2
	v_exp_f32_e32 v142, v50
	v_exp_f32_e32 v154, v2
	v_sub_f32_e32 v2, v12, v113
	v_exp_f32_e32 v50, v107
	v_mul_f32_e32 v2, 0x3fb8aa3b, v2
	v_exp_f32_e32 v112, v2
	v_sub_f32_e32 v2, v13, v113
	v_mul_f32_e32 v2, 0x3fb8aa3b, v2
	v_exp_f32_e32 v114, v2
	v_sub_f32_e32 v2, v14, v113
	v_pk_mul_f32 v[8:9], v[40:41], v[50:51] op_sel_hi:[1,0]
	v_pk_mul_f32 v[6:7], v[38:39], v[50:51] op_sel_hi:[1,0]
	ds_read2_b64 v[38:41], v194 offset1:2
	v_mul_f32_e32 v2, 0x3fb8aa3b, v2
	v_exp_f32_e32 v116, v2
	v_sub_f32_e32 v2, v15, v113
	v_mul_f32_e32 v2, 0x3fb8aa3b, v2
	v_exp_f32_e32 v118, v2
	v_sub_f32_e32 v2, v16, v113
	v_mul_f32_e32 v2, 0x3fb8aa3b, v2
	v_exp_f32_e32 v120, v2
	v_sub_f32_e32 v2, v17, v113
	v_mul_f32_e32 v2, 0x3fb8aa3b, v2
	v_exp_f32_e32 v122, v2
	v_pk_mul_f32 v[16:17], v[48:49], v[50:51] op_sel_hi:[1,0]
	v_pk_mul_f32 v[14:15], v[46:47], v[50:51] op_sel_hi:[1,0]
	v_pk_mul_f32 v[12:13], v[44:45], v[50:51] op_sel_hi:[1,0]
	v_pk_mul_f32 v[10:11], v[42:43], v[50:51] op_sel_hi:[1,0]
	v_pk_mul_f32 v[4:5], v[36:37], v[50:51] op_sel_hi:[1,0]
	v_pk_mul_f32 v[2:3], v[34:35], v[50:51] op_sel_hi:[1,0]
	v_cvt_pk_bf16_f32 v34, v115, v51
	v_cvt_pk_bf16_f32 v35, v158, v160
	v_cvt_pk_bf16_f32 v36, v162, v164
	v_cvt_pk_bf16_f32 v37, v166, v168
	v_pk_mul_f32 v[32:33], v[32:33], v[50:51] op_sel_hi:[1,0]
	s_waitcnt lgkmcnt(0)
	v_mfma_f32_32x32x16_bf16 v[2:17], v[38:41], v[34:37], v[2:17]
	ds_read2_b64 v[38:41], v193 offset1:2
	ds_read2_b64 v[42:45], v193 offset0:4 offset1:6
	v_mul_f32_e64 v30, v30, v50
	v_mul_f32_e64 v31, v31, v50
	v_mul_f32_e64 v28, v28, v50
	v_mul_f32_e64 v29, v29, v50
	v_pk_mul_f32 v[26:27], v[26:27], v[50:51] op_sel_hi:[1,0]
	v_pk_mul_f32 v[24:25], v[24:25], v[50:51] op_sel_hi:[1,0]
	v_pk_mul_f32 v[22:23], v[22:23], v[50:51] op_sel_hi:[1,0]
	v_pk_mul_f32 v[20:21], v[20:21], v[50:51] op_sel_hi:[1,0]
	v_pk_mul_f32 v[18:19], v[18:19], v[50:51] op_sel_hi:[1,0]
	v_mul_f32_e32 v156, v156, v50
	v_mov_b32_e32 v107, v1
	s_waitcnt lgkmcnt(1)
	v_mfma_f32_32x32x16_bf16 v[18:33], v[38:41], v[34:37], v[18:33]
	ds_read2_b64 v[38:41], v194 offset0:4 offset1:6
	v_cvt_pk_bf16_f32 v34, v170, v172
	v_cvt_pk_bf16_f32 v35, v124, v126
	v_cvt_pk_bf16_f32 v36, v130, v134
	v_cvt_pk_bf16_f32 v37, v138, v142
	s_waitcnt lgkmcnt(0)
	v_mfma_f32_32x32x16_bf16 v[2:17], v[38:41], v[34:37], v[2:17]
	ds_read2_b64 v[38:41], v194 offset0:8 offset1:10
	v_mfma_f32_32x32x16_bf16 v[18:33], v[42:45], v[34:37], v[18:33]
	v_cvt_pk_bf16_f32 v34, v146, v150
	v_cvt_pk_bf16_f32 v35, v128, v132
	v_cvt_pk_bf16_f32 v36, v136, v140
	v_cvt_pk_bf16_f32 v37, v144, v148
	s_waitcnt lgkmcnt(0)
	v_mfma_f32_32x32x16_bf16 v[2:17], v[38:41], v[34:37], v[2:17]
	ds_read2_b64 v[38:41], v193 offset0:8 offset1:10
	s_waitcnt lgkmcnt(0)
	v_mfma_f32_32x32x16_bf16 v[18:33], v[38:41], v[34:37], v[18:33]
	ds_read2_b64 v[38:41], v194 offset0:12 offset1:14
	v_cvt_pk_bf16_f32 v34, v152, v154
	v_cvt_pk_bf16_f32 v35, v112, v114
	v_cvt_pk_bf16_f32 v36, v116, v118
	v_cvt_pk_bf16_f32 v37, v120, v122
	s_waitcnt lgkmcnt(0)
	v_mfma_f32_32x32x16_bf16 v[2:17], v[38:41], v[34:37], v[2:17]
	ds_read2_b64 v[38:41], v193 offset0:12 offset1:14
	s_waitcnt lgkmcnt(0)
	v_mfma_f32_32x32x16_bf16 v[18:33], v[38:41], v[34:37], v[18:33]
	ds_read_b128 v[34:37], v91 offset:27648
	s_waitcnt lgkmcnt(0)
; #define LAS __attribute__((address_space(3)))
; __device__ __forceinline__ void attn_chunk(LAS unsigned char* Kl, LAS unsigned char* Vl, const bf16x8 (&qf)[4], f32x16 (&o)[2], float& m, float& l, int q, int half, int ii, int maskmode) {
;     ...
;     for (int kb = 0; kb < 2; ++kb) {
; #pragma unroll
;         for (int r = 0; r < 16; ++r) s[kb][r] = 0.f;
; #pragma unroll
;         for (int ks = 0; ks < 4; ++ks) { const bf16x8 kf = *(const LAS bf16x8*)(Kl + (32 * kb + q) * 144 + (2 * ks + half) * 16); s[kb] = __builtin_amdgcn_mfma_f32_32x32x16_bf16(kf, qf[ks], s[kb], 0, 0, 0); }
;     }
;     if (maskmode != 0) {
; #pragma unroll
;         for (int kb = 0; kb < 2; ++kb)
; #pragma unroll
;             for (int r = 0; r < 16; ++r) { const int jj = 32 * kb + 8 * (r >> 2) + 4 * half + (r & 3); const bool ok = (maskmode == 1) ? (jj >= ii) : (jj <= ii); if (!ok) s[kb][r] = -1e30f; }
;     }
;     float mx = s[0][0];
; #pragma unroll
;     for (int kb = 0; kb < 2; ++kb)
; #pragma unroll
;         for (int r = 0; r < 16; ++r) mx = fmaxf(mx, s[kb][r]);
;     mx = fmaxf(mx, __shfl_xor(mx, 32));
;     const float mn = fmaxf(m, mx), alpha = __expf(m - mn);
;     float ps = 0.f;
; #pragma unroll
;     for (int kb = 0; kb < 2; ++kb)
; #pragma unroll
;         for (int r = 0; r < 16; ++r) { const float p = __expf(s[kb][r] - mn); s[kb][r] = p; ps += p; }
;     l = l * alpha + ps; m = mn;
	v_mfma_f32_32x32x16_bf16 v[50:65], v[34:37], v[78:81], 0
	ds_read_b128 v[34:37], v91 offset:27680
	s_waitcnt lgkmcnt(0)
	v_mfma_f32_32x32x16_bf16 v[50:65], v[34:37], v[74:77], v[50:65]
	ds_read_b128 v[34:37], v91 offset:27712
	s_waitcnt lgkmcnt(0)
	v_mfma_f32_32x32x16_bf16 v[50:65], v[34:37], v[70:73], v[50:65]
	ds_read_b128 v[34:37], v91 offset:27744
	s_waitcnt lgkmcnt(0)
	v_mfma_f32_32x32x16_bf16 v[50:65], v[34:37], v[66:69], v[50:65]
	ds_read_b128 v[34:37], v91 offset:32256
	s_waitcnt lgkmcnt(0)
	v_mfma_f32_32x32x16_bf16 v[34:49], v[34:37], v[78:81], 0
	ds_read_b128 v[78:81], v91 offset:32288
	s_waitcnt lgkmcnt(0)
	v_mfma_f32_32x32x16_bf16 v[34:49], v[78:81], v[74:77], v[34:49]
	ds_read_b128 v[74:77], v91 offset:32320
	s_waitcnt lgkmcnt(0)
	v_mfma_f32_32x32x16_bf16 v[34:49], v[74:77], v[70:73], v[34:49]
	ds_read_b128 v[70:73], v91 offset:32352
	s_waitcnt lgkmcnt(0)
	v_mfma_f32_32x32x16_bf16 v[34:49], v[70:73], v[66:69], v[34:49]
	v_max_f32_e32 v66, v51, v51
	v_max_f32_e32 v67, v50, v50
	v_max_f32_e32 v66, v67, v66
	v_max3_f32 v66, v66, v52, v53
	v_max3_f32 v66, v66, v54, v55
	v_max3_f32 v66, v66, v56, v57
	v_max3_f32 v66, v66, v58, v59
	v_max3_f32 v66, v66, v60, v61
	v_max3_f32 v66, v66, v62, v63
	v_max3_f32 v66, v66, v64, v65
	s_nop 1
	v_max3_f32 v66, v66, v34, v35
	v_max3_f32 v66, v66, v36, v37
	v_max3_f32 v66, v66, v38, v39
	v_max3_f32 v66, v66, v40, v41
	v_max3_f32 v66, v66, v42, v43
	v_max3_f32 v66, v66, v44, v45
	v_max3_f32 v66, v66, v46, v47
	v_max3_f32 v66, v66, v48, v49
	ds_bpermute_b32 v67, v177, v66
	s_waitcnt lgkmcnt(0)
	v_max3_f32 v66, v113, v66, v67
	v_sub_f32_e32 v50, v50, v66
	v_mul_f32_e32 v50, 0x3fb8aa3b, v50
	v_exp_f32_e32 v159, v50
	v_sub_f32_e32 v50, v51, v66
	v_mul_f32_e32 v50, 0x3fb8aa3b, v50
	v_exp_f32_e32 v161, v50
	v_sub_f32_e32 v50, v52, v66
	v_mul_f32_e32 v50, 0x3fb8aa3b, v50
	v_exp_f32_e32 v163, v50
	v_sub_f32_e32 v50, v53, v66
	v_mul_f32_e32 v50, 0x3fb8aa3b, v50
	v_exp_f32_e32 v165, v50
	v_sub_f32_e32 v50, v54, v66
	v_mul_f32_e32 v50, 0x3fb8aa3b, v50
	v_exp_f32_e32 v167, v50
	v_sub_f32_e32 v50, v55, v66
	v_mul_f32_e32 v50, 0x3fb8aa3b, v50
	v_exp_f32_e32 v169, v50
	v_sub_f32_e32 v50, v56, v66
	v_mul_f32_e32 v50, 0x3fb8aa3b, v50
	v_exp_f32_e32 v171, v50
	v_sub_f32_e32 v50, v57, v66
	v_mul_f32_e32 v50, 0x3fb8aa3b, v50
	v_sub_f32_e32 v52, v59, v66
	v_exp_f32_e32 v173, v50
	v_sub_f32_e32 v50, v58, v66
	v_mul_f32_e32 v52, 0x3fb8aa3b, v52
	v_mul_f32_e32 v50, 0x3fb8aa3b, v50
	v_exp_f32_e32 v127, v52
	v_sub_f32_e32 v52, v60, v66
	v_sub_f32_e32 v34, v34, v66
	v_exp_f32_e32 v125, v50
	v_pk_add_f32 v[50:51], v[158:159], v[174:175]
	v_mul_f32_e32 v52, 0x3fb8aa3b, v52
	v_mul_f32_e32 v34, 0x3fb8aa3b, v34
	v_pk_add_f32 v[50:51], v[160:161], v[50:51]
	v_exp_f32_e32 v131, v52
	v_sub_f32_e32 v52, v61, v66
	v_exp_f32_e32 v129, v34
	v_sub_f32_e32 v34, v35, v66
	v_pk_add_f32 v[50:51], v[162:163], v[50:51]
	v_mul_f32_e32 v52, 0x3fb8aa3b, v52
	v_mul_f32_e32 v34, 0x3fb8aa3b, v34
	v_pk_add_f32 v[50:51], v[164:165], v[50:51]
	v_exp_f32_e32 v135, v52
	v_sub_f32_e32 v52, v62, v66
	v_exp_f32_e32 v133, v34
	v_sub_f32_e32 v34, v36, v66
	v_sub_f32_e32 v36, v38, v66
	v_pk_add_f32 v[50:51], v[166:167], v[50:51]
	v_mul_f32_e32 v52, 0x3fb8aa3b, v52
	v_mul_f32_e32 v36, 0x3fb8aa3b, v36
	v_pk_add_f32 v[50:51], v[168:169], v[50:51]
	v_exp_f32_e32 v139, v52
	v_sub_f32_e32 v52, v63, v66
	v_exp_f32_e32 v145, v36
	v_sub_f32_e32 v36, v39, v66
	v_pk_add_f32 v[50:51], v[170:171], v[50:51]
	v_mul_f32_e32 v52, 0x3fb8aa3b, v52
	v_mul_f32_e32 v34, 0x3fb8aa3b, v34
	v_mul_f32_e32 v36, 0x3fb8aa3b, v36
	v_pk_add_f32 v[50:51], v[172:173], v[50:51]
	v_exp_f32_e32 v143, v52
	v_sub_f32_e32 v52, v64, v66
	v_exp_f32_e32 v137, v34
	v_sub_f32_e32 v34, v37, v66
	v_exp_f32_e32 v149, v36
	v_sub_f32_e32 v36, v40, v66
	v_pk_add_f32 v[50:51], v[124:125], v[50:51]
	v_mul_f32_e32 v52, 0x3fb8aa3b, v52
	v_mul_f32_e32 v34, 0x3fb8aa3b, v34
	v_mul_f32_e32 v36, 0x3fb8aa3b, v36
	v_exp_f32_e32 v147, v52
	v_sub_f32_e32 v52, v65, v66
	v_exp_f32_e32 v141, v34
	v_pk_add_f32 v[34:35], v[126:127], v[50:51]
	v_exp_f32_e32 v153, v36
	v_sub_f32_e32 v36, v41, v66
	v_mul_f32_e32 v52, 0x3fb8aa3b, v52
	v_pk_add_f32 v[34:35], v[130:131], v[34:35]
	v_mul_f32_e32 v36, 0x3fb8aa3b, v36
	v_exp_f32_e32 v151, v52
	v_pk_add_f32 v[34:35], v[134:135], v[34:35]
	v_exp_f32_e32 v155, v36
	v_sub_f32_e32 v36, v42, v66
	v_pk_add_f32 v[34:35], v[138:139], v[34:35]
	v_mul_f32_e32 v36, 0x3fb8aa3b, v36
	v_sub_f32_e32 v67, v113, v66
	v_pk_add_f32 v[34:35], v[142:143], v[34:35]
	v_exp_f32_e32 v113, v36
	v_sub_f32_e32 v36, v43, v66
	v_pk_add_f32 v[34:35], v[146:147], v[34:35]
	v_mul_f32_e32 v36, 0x3fb8aa3b, v36
	v_pk_add_f32 v[34:35], v[150:151], v[34:35]
	v_exp_f32_e32 v115, v36
	v_sub_f32_e32 v36, v44, v66
	v_pk_add_f32 v[34:35], v[128:129], v[34:35]
	v_mul_f32_e32 v36, 0x3fb8aa3b, v36
	v_pk_add_f32 v[34:35], v[132:133], v[34:35]
	v_exp_f32_e32 v117, v36
	v_sub_f32_e32 v36, v45, v66
	v_pk_add_f32 v[34:35], v[136:137], v[34:35]
	v_mul_f32_e32 v36, 0x3fb8aa3b, v36
	v_pk_add_f32 v[34:35], v[140:141], v[34:35]
	v_exp_f32_e32 v119, v36
	v_sub_f32_e32 v36, v46, v66
	v_mul_f32_e32 v36, 0x3fb8aa3b, v36
	v_pk_add_f32 v[34:35], v[144:145], v[34:35]
	v_exp_f32_e32 v121, v36
	v_sub_f32_e32 v36, v47, v66
	v_pk_add_f32 v[34:35], v[148:149], v[34:35]
	v_mul_f32_e32 v36, 0x3fb8aa3b, v36
	v_pk_add_f32 v[34:35], v[152:153], v[34:35]
	v_exp_f32_e32 v123, v36
	v_sub_f32_e32 v36, v48, v66
	v_pk_add_f32 v[34:35], v[154:155], v[34:35]
	v_mul_f32_e32 v67, 0x3fb8aa3b, v67
	v_mul_f32_e32 v36, 0x3fb8aa3b, v36
	v_pk_add_f32 v[34:35], v[112:113], v[34:35]
	v_exp_f32_e32 v157, v36
	v_sub_f32_e32 v36, v49, v66
	v_exp_f32_e32 v52, v67
; #define LAS __attribute__((address_space(3)))
; __device__ __forceinline__ unsigned pk2(float lo, float hi) { unsigned r; asm("v_cvt_pk_bf16_f32 %0, %1, %2" : "=v"(r) : "v"(lo), "v"(hi)); return r; }
; __device__ __forceinline__ void attn_chunk(LAS unsigned char* Kl, LAS unsigned char* Vl, const bf16x8 (&qf)[4], f32x16 (&o)[2], float& m, float& l, int q, int half, int ii, int maskmode) {
;     ...
; #pragma unroll
;     for (int db = 0; db < 2; ++db)
; #pragma unroll
;         for (int r = 0; r < 16; ++r) o[db][r] *= alpha;
; #pragma unroll
;     for (int kb = 0; kb < 2; ++kb)
; #pragma unroll
;         for (int t = 0; t < 2; ++t) {
;             union { bf16x8 v; unsigned u[4]; } pf;
; #pragma unroll
;             for (int i = 0; i < 4; ++i) pf.u[i] = pk2(s[kb][8 * t + 2 * i], s[kb][8 * t + 2 * i + 1]);
; #pragma unroll
;             for (int db = 0; db < 2; ++db) {
;                 union { bf16x8 v; u32x2 h[2]; } vf;
;                 const LAS unsigned char* vp = Vl + (32 * db + q) * 136 + (32 * kb + 16 * t + 4 * half) * 2;
;                 vf.h[0] = *(const LAS u32x2*)vp; vf.h[1] = *(const LAS u32x2*)(vp + 16);
;                 o[db] = __builtin_amdgcn_mfma_f32_32x32x16_bf16(vf.v, pf.v, o[db], 0, 0, 0);
;             }
;         }
; }
; __device__ __forceinline__ void attn_phase(const Params& P, LAS unsigned char* lds) {
;     ...
;         __syncthreads();
;         const float lt = l + __shfl_xor(l, 32), inv = 1.f / lt;
;         bf16_t* op = ao + (size_t)tok * D + h * 64;
; #pragma unroll
;         for (int db = 0; db < 2; ++db)
; #pragma unroll
;             for (int rg = 0; rg < 4; ++rg) { u32x2 ov; ov.x = pk2(o[db][4 * rg] * inv, o[db][4 * rg + 1] * inv); ov.y = pk2(o[db][4 * rg + 2] * inv, o[db][4 * rg + 3] * inv);
;                 *(u32x2*)(op + 32 * db + 8 * rg + 4 * half) = ov; }
;     }
	v_pk_add_f32 v[34:35], v[114:115], v[34:35]
	v_mul_f32_e32 v36, 0x3fb8aa3b, v36
	v_pk_add_f32 v[34:35], v[116:117], v[34:35]
	v_exp_f32_e32 v51, v36
	v_pk_add_f32 v[34:35], v[118:119], v[34:35]
	v_pk_mul_f32 v[44:45], v[12:13], v[52:53] op_sel_hi:[1,0]
	v_pk_add_f32 v[34:35], v[120:121], v[34:35]
	v_pk_mul_f32 v[42:43], v[10:11], v[52:53] op_sel_hi:[1,0]
	v_pk_add_f32 v[34:35], v[122:123], v[34:35]
	v_pk_mul_f32 v[40:41], v[8:9], v[52:53] op_sel_hi:[1,0]
	v_pk_mul_f32 v[38:39], v[6:7], v[52:53] op_sel_hi:[1,0]
	v_pk_mul_f32 v[12:13], v[28:29], v[52:53] op_sel_hi:[1,0]
	v_pk_mul_f32 v[10:11], v[26:27], v[52:53] op_sel_hi:[1,0]
	v_pk_mul_f32 v[8:9], v[24:25], v[52:53] op_sel_hi:[1,0]
	v_pk_mul_f32 v[6:7], v[22:23], v[52:53] op_sel_hi:[1,0]
	ds_read2_b64 v[22:25], v216 offset0:192 offset1:194
	ds_read2_b64 v[26:29], v216 offset0:196 offset1:198
	v_pk_add_f32 v[34:35], v[156:157], v[34:35]
	v_pk_mul_f32 v[48:49], v[16:17], v[52:53] op_sel_hi:[1,0]
	v_add_f32_e32 v50, v35, v51
	v_fmac_f32_e32 v50, v34, v52
	v_pk_mul_f32 v[46:47], v[14:15], v[52:53] op_sel_hi:[1,0]
	v_pk_mul_f32 v[36:37], v[4:5], v[52:53] op_sel_hi:[1,0]
	v_pk_mul_f32 v[34:35], v[2:3], v[52:53] op_sel_hi:[1,0]
	v_pk_mul_f32 v[4:5], v[20:21], v[52:53] op_sel_hi:[1,0]
	v_pk_mul_f32 v[2:3], v[18:19], v[52:53] op_sel_hi:[1,0]
	v_cvt_pk_bf16_f32 v18, v159, v161
	v_cvt_pk_bf16_f32 v19, v163, v165
	v_cvt_pk_bf16_f32 v20, v167, v169
	v_cvt_pk_bf16_f32 v21, v171, v173
	v_pk_mul_f32 v[16:17], v[32:33], v[52:53] op_sel_hi:[1,0]
	s_waitcnt lgkmcnt(1)
	v_mfma_f32_32x32x16_bf16 v[34:49], v[22:25], v[18:21], v[34:49]
	ds_read2_b64 v[22:25], v195 offset0:224 offset1:226
	v_mul_f32_e64 v14, v30, v52
	v_mul_f32_e64 v15, v31, v52
	s_waitcnt lgkmcnt(0)
	s_nop 0
	v_mfma_f32_32x32x16_bf16 v[2:17], v[22:25], v[18:21], v[2:17]
	ds_read2_b64 v[22:25], v195 offset0:228 offset1:230
	v_cvt_pk_bf16_f32 v18, v125, v127
	v_cvt_pk_bf16_f32 v19, v131, v135
	v_cvt_pk_bf16_f32 v20, v139, v143
	v_cvt_pk_bf16_f32 v21, v147, v151
	s_waitcnt lgkmcnt(0)
	v_mfma_f32_32x32x16_bf16 v[2:17], v[22:25], v[18:21], v[2:17]
	ds_read2_b64 v[22:25], v216 offset0:200 offset1:202
	v_mfma_f32_32x32x16_bf16 v[34:49], v[26:29], v[18:21], v[34:49]
	v_cvt_pk_bf16_f32 v18, v129, v133
	v_cvt_pk_bf16_f32 v19, v137, v141
	v_cvt_pk_bf16_f32 v20, v145, v149
	v_cvt_pk_bf16_f32 v21, v153, v155
	s_waitcnt lgkmcnt(0)
	v_mfma_f32_32x32x16_bf16 v[34:49], v[22:25], v[18:21], v[34:49]
	ds_read2_b64 v[22:25], v195 offset0:232 offset1:234
	s_waitcnt lgkmcnt(0)
	v_mfma_f32_32x32x16_bf16 v[2:17], v[22:25], v[18:21], v[2:17]
	ds_read2_b64 v[22:25], v216 offset0:204 offset1:206
	v_cvt_pk_bf16_f32 v18, v113, v115
	v_cvt_pk_bf16_f32 v19, v117, v119
	v_cvt_pk_bf16_f32 v20, v121, v123
	v_cvt_pk_bf16_f32 v21, v157, v51
	s_waitcnt lgkmcnt(0)
	v_mfma_f32_32x32x16_bf16 v[34:49], v[22:25], v[18:21], v[34:49]
	ds_read2_b64 v[22:25], v195 offset0:236 offset1:238
	s_waitcnt lgkmcnt(0)
	s_barrier
	v_mfma_f32_32x32x16_bf16 v[2:17], v[22:25], v[18:21], v[2:17]
	ds_bpermute_b32 v18, v177, v50
	s_waitcnt lgkmcnt(0)
	v_add_f32_e32 v18, v50, v18
	v_div_scale_f32 v19, s[0:1], v18, v18, 1.0
	v_rcp_f32_e32 v20, v19
	v_readlane_b32 s0, v250, 27
	v_readlane_b32 s1, v250, 28
	v_fma_f32 v21, -v19, v20, 1.0
	v_fmac_f32_e32 v20, v21, v20
	v_div_scale_f32 v21, vcc, 1.0, v18, 1.0
	v_mul_f32_e32 v22, v21, v20
	v_fma_f32 v23, -v19, v22, v21
	v_fmac_f32_e32 v22, v23, v20
	v_fma_f32 v19, -v19, v22, v21
	v_div_fmas_f32 v19, v19, v20, v22
	v_div_fixup_f32 v22, v19, v18, 1.0
	v_lshlrev_b64 v[18:19], 11, v[108:109]
	v_lshl_add_u64 v[18:19], s[0:1], 0, v[18:19]
	v_mul_f32_e32 v20, v34, v22
	v_mul_f32_e32 v21, v35, v22
	v_mul_f32_e32 v2, v2, v22
	v_mul_f32_e32 v3, v3, v22
	v_lshl_add_u64 v[18:19], v[110:111], 1, v[18:19]
	v_cvt_pk_bf16_f32 v20, v20, v21
	v_mul_f32_e32 v21, v36, v22
	v_cvt_pk_bf16_f32 v2, v2, v3
	v_mul_f32_e32 v3, v4, v22
	v_lshl_add_u64 v[18:19], v[18:19], 0, v[106:107]
	v_mul_f32_e32 v23, v37, v22
	v_cvt_pk_bf16_f32 v21, v21, v23
	v_mul_f32_e32 v4, v5, v22
	v_cvt_pk_bf16_f32 v3, v3, v4
	global_store_dwordx2 v[18:19], v[20:21], off
	v_mul_f32_e32 v20, v38, v22
	v_mul_f32_e32 v21, v39, v22
	global_store_dwordx2 v[18:19], v[2:3], off offset:64
	v_mul_f32_e32 v2, v6, v22
	v_mul_f32_e32 v3, v7, v22
	v_cvt_pk_bf16_f32 v20, v20, v21
	v_mul_f32_e32 v21, v40, v22
	v_cvt_pk_bf16_f32 v2, v2, v3
	v_mul_f32_e32 v3, v8, v22
	v_mul_f32_e32 v23, v41, v22
	v_cvt_pk_bf16_f32 v21, v21, v23
	v_mul_f32_e32 v4, v9, v22
	v_cvt_pk_bf16_f32 v3, v3, v4
	global_store_dwordx2 v[18:19], v[20:21], off offset:16
	v_mul_f32_e32 v20, v42, v22
	v_mul_f32_e32 v21, v43, v22
	global_store_dwordx2 v[18:19], v[2:3], off offset:80
	v_mul_f32_e32 v2, v10, v22
	v_mul_f32_e32 v3, v11, v22
	v_cvt_pk_bf16_f32 v20, v20, v21
	v_mul_f32_e32 v21, v44, v22
	v_cvt_pk_bf16_f32 v2, v2, v3
	v_mul_f32_e32 v3, v12, v22
	v_mul_f32_e32 v23, v45, v22
	v_cvt_pk_bf16_f32 v21, v21, v23
	v_mul_f32_e32 v4, v13, v22
	v_cvt_pk_bf16_f32 v3, v3, v4
	global_store_dwordx2 v[18:19], v[20:21], off offset:32
	v_mul_f32_e32 v20, v46, v22
	v_mul_f32_e32 v21, v47, v22
	global_store_dwordx2 v[18:19], v[2:3], off offset:96
	v_mul_f32_e32 v2, v14, v22
	v_mul_f32_e32 v3, v15, v22
	v_cvt_pk_bf16_f32 v20, v20, v21
	v_mul_f32_e32 v21, v48, v22
	v_cvt_pk_bf16_f32 v2, v2, v3
	v_mul_f32_e32 v3, v16, v22
	v_mul_f32_e32 v23, v49, v22
	v_cvt_pk_bf16_f32 v21, v21, v23
	global_store_dwordx2 v[18:19], v[20:21], off offset:48
	v_mul_f32_e32 v4, v17, v22
	v_cvt_pk_bf16_f32 v3, v3, v4
	global_store_dwordx2 v[18:19], v[2:3], off offset:112
	s_load_dword s0, s[50:51], 0x0
	s_waitcnt lgkmcnt(0)
	s_add_i32 s34, s0, s34
	s_cmpk_gt_i32 s34, 0x3ff
	s_cbranch_scc1 .LBB0_744
; __device__ __forceinline__ float bflo(unsigned u) { return __uint_as_float(u << 16); }
; __device__ __forceinline__ float bfhi(unsigned u) { return __uint_as_float(u & 0xFFFF0000u); }
; __device__ __forceinline__ void attn_phase(const Params& P, LAS unsigned char* lds) {
;     ...
;         const int qb = unit >> 2, g = unit & 3, h = 4 * g + (wave >> 1), ii = 32 * (wave & 1) + q, tok = 64 * qb + ii;
;         bf16x8 qf[4];
;         {
;             float yq[4][8]; float ss = 0.f;
; #pragma unroll
;             for (int ks = 0; ks < 4; ++ks) { const u32x4 raw = *(const u32x4*)(qk + (size_t)tok * 1280 + h * 64 + 16 * ks + 8 * half);
;                 yq[ks][0] = bflo(raw.x); yq[ks][1] = bfhi(raw.x); yq[ks][2] = bflo(raw.y); yq[ks][3] = bfhi(raw.y); yq[ks][4] = bflo(raw.z); yq[ks][5] = bfhi(raw.z); yq[ks][6] = bflo(raw.w); yq[ks][7] = bfhi(raw.w);
; #pragma unroll
;                 for (int i = 0; i < 8; ++i) ss += yq[ks][i] * yq[ks][i]; }
;             ss += __shfl_xor(ss, 32);
;             const float rs = rsqrtf(ss * (1.f / 64.f) + 1e-6f) * 0.125f;
; #pragma unroll
;             for (int ks = 0; ks < 4; ++ks) { const f32x4 g0 = *(const f32x4*)(P.q_gain + 16 * ks + 8 * half), g1 = *(const f32x4*)(P.q_gain + 16 * ks + 8 * half + 4);
; #pragma unroll
;                 for (int i = 0; i < 4; ++i) { yq[ks][i] *= rs * g0[i]; yq[ks][4 + i] *= rs * g1[i]; } }
;             const float2* cr = rope + (tok >> 6) * 16 + 8 * half; const float2* cc = rope + (tok & 63) * 16 + 8 * half;
.LBB0_724:
	s_ashr_i32 s18, s34, 2
	s_and_b32 s8, s34, 3
	v_readlane_b32 s46, v250, 31
	s_waitcnt vmcnt(0)
	v_lshl_add_u32 v54, s8, 2, v87
	s_lshl_b32 s0, s18, 6
	v_readlane_b32 s47, v250, 32
	v_or_b32_e32 v108, s0, v176
	s_movk_i32 s3, 0xa00
	v_mov_b64_e32 v[2:3], s[46:47]
	v_lshlrev_b32_e32 v110, 6, v54
	global_load_dwordx4 v[56:59], v[102:103], off offset:192
	global_load_dwordx4 v[60:63], v[102:103], off offset:208
	global_load_dwordx4 v[30:33], v[102:103], off offset:128
	global_load_dwordx4 v[26:29], v[102:103], off offset:144
	v_mad_i64_i32 v[2:3], s[14:15], v108, s3, v[2:3]
	v_ashrrev_i32_e32 v111, 31, v110
	global_load_dwordx4 v[50:53], v[102:103], off offset:80
	global_load_dwordx4 v[38:41], v[102:103], off offset:16
	v_lshl_add_u64 v[2:3], v[110:111], 1, v[2:3]
	v_lshl_add_u64 v[2:3], v[2:3], 0, v[0:1]
	global_load_dwordx4 v[64:67], v[2:3], off offset:64
	global_load_dwordx4 v[68:71], v[2:3], off offset:96
	global_load_dwordx4 v[72:75], v[2:3], off
	global_load_dwordx4 v[76:79], v[2:3], off offset:32
	global_load_dwordx4 v[42:45], v[102:103], off
	global_load_dwordx4 v[46:49], v[102:103], off offset:64
	s_nop 0
	global_load_dwordx4 v[2:5], v[84:85], off offset:48
	global_load_dwordx4 v[6:9], v[84:85], off offset:32
	global_load_dwordx4 v[10:13], v[84:85], off offset:16
	global_load_dwordx4 v[14:17], v[84:85], off
	s_lshl_b32 s14, s18, 4
	s_ashr_i32 s15, s14, 31
	v_lshl_add_u64 v[80:81], s[14:15], 3, v[82:83]
	global_load_dwordx4 v[18:21], v[80:81], off offset:48
	global_load_dwordx4 v[22:25], v[80:81], off offset:32
	global_load_dwordx4 v[34:37], v[80:81], off offset:16
	global_load_dwordx4 v[112:115], v[80:81], off
	v_readlane_b32 s76, v252, 52
	v_readlane_b32 s84, v252, 60
	v_readlane_b32 s85, v252, 61
	s_lshl_b32 s35, s8, 6
	s_add_i32 s1, s18, -2
	s_cmpk_lt_u32 s1, 0x100
	v_add_u32_e32 v107, v184, v90
	v_readlane_b32 s77, v252, 53
	v_readlane_b32 s78, v252, 54
	v_readlane_b32 s79, v252, 55
	v_readlane_b32 s80, v252, 56
	v_readlane_b32 s81, v252, 57
	v_readlane_b32 s82, v252, 58
	v_readlane_b32 s83, v252, 59
	v_readlane_b32 s86, v252, 62
	v_readlane_b32 s87, v252, 63
	v_readlane_b32 s88, v253, 0
	v_readlane_b32 s89, v253, 1
	v_readlane_b32 s90, v253, 2
	v_readlane_b32 s91, v253, 3
	s_waitcnt vmcnt(13)
	v_and_b32_e32 v117, 0xffff0000, v67
	s_waitcnt vmcnt(12)
	v_lshlrev_b32_e32 v118, 16, v70
	s_waitcnt vmcnt(11)
	v_lshlrev_b32_e32 v147, 16, v73
	v_and_b32_e32 v151, 0xffff0000, v73
	v_lshlrev_b32_e32 v155, 16, v72
	s_waitcnt vmcnt(10)
	v_lshlrev_b32_e32 v154, 16, v76
	v_and_b32_e32 v73, 0xffff0000, v72
	v_and_b32_e32 v72, 0xffff0000, v76
	v_lshlrev_b32_e32 v146, 16, v77
	v_and_b32_e32 v150, 0xffff0000, v77
	v_pk_mul_f32 v[156:157], v[154:155], v[154:155]
	v_pk_mul_f32 v[76:77], v[72:73], v[72:73]
	v_mov_b32_e32 v144, v50
	v_pk_mul_f32 v[148:149], v[146:147], v[146:147]
	v_add_f32_e32 v50, v157, v77
	v_lshlrev_b32_e32 v127, 16, v74
	v_lshlrev_b32_e32 v126, 16, v78
	v_pk_mul_f32 v[152:153], v[150:151], v[150:151]
	v_add_f32_e32 v50, v149, v50
	v_mov_b32_e32 v81, v28
	v_mov_b32_e32 v28, v63
	v_mov_b32_e32 v63, v26
	v_mov_b32_e32 v26, v61
	v_mov_b32_e32 v61, v32
	v_mov_b32_e32 v32, v59
	v_mov_b32_e32 v59, v30
	v_mov_b32_e32 v30, v57
	v_mov_b32_e32 v57, v40
	v_mov_b32_e32 v40, v53
	v_lshlrev_b32_e32 v53, 16, v67
	v_lshlrev_b32_e32 v119, 16, v66
	v_and_b32_e32 v67, 0xffff0000, v66
	v_and_b32_e32 v66, 0xffff0000, v70
	v_lshlrev_b32_e32 v70, 16, v69
	v_and_b32_e32 v120, 0xffff0000, v69
	v_lshlrev_b32_e32 v69, 16, v75
	v_and_b32_e32 v125, 0xffff0000, v75
	v_pk_mul_f32 v[142:143], v[126:127], v[126:127]
	v_and_b32_e32 v75, 0xffff0000, v74
	v_and_b32_e32 v74, 0xffff0000, v78
	v_add_f32_e32 v50, v153, v50
	v_mov_b32_e32 v80, v62
	v_mov_b32_e32 v62, v60
	v_mov_b32_e32 v60, v58
	v_mov_b32_e32 v58, v56
	v_mov_b32_e32 v56, v52
	v_lshlrev_b32_e32 v52, 16, v71
	v_and_b32_e32 v116, 0xffff0000, v71
	v_lshlrev_b32_e32 v71, 16, v65
	v_and_b32_e32 v121, 0xffff0000, v65
	v_lshlrev_b32_e32 v122, 16, v68
	v_lshlrev_b32_e32 v123, 16, v64
	v_and_b32_e32 v65, 0xffff0000, v64
	v_and_b32_e32 v64, 0xffff0000, v68
	v_lshlrev_b32_e32 v68, 16, v79
	v_and_b32_e32 v124, 0xffff0000, v79
	v_pk_mul_f32 v[78:79], v[74:75], v[74:75]
	v_add_f32_e32 v50, v143, v50
	v_pk_mul_f32 v[138:139], v[68:69], v[68:69]
	v_add_f32_e32 v50, v79, v50
	v_pk_mul_f32 v[140:141], v[124:125], v[124:125]
	v_add_f32_e32 v50, v139, v50
	v_add_f32_e32 v50, v141, v50
	v_add_f32_e32 v50, v156, v50
	v_add_f32_e32 v50, v76, v50
	v_add_f32_e32 v50, v148, v50
	v_add_f32_e32 v50, v152, v50
	v_add_f32_e32 v50, v142, v50
	v_add_f32_e32 v50, v78, v50
	v_add_f32_e32 v50, v138, v50
	v_add_f32_e32 v50, v140, v50
	v_fmac_f32_e32 v50, v123, v123
	v_fmac_f32_e32 v50, v65, v65
	v_fmac_f32_e32 v50, v71, v71
	v_fmac_f32_e32 v50, v121, v121
	v_mov_b32_e32 v128, v117
	v_mov_b32_e32 v129, v53
	v_fmac_f32_e32 v50, v119, v119
	v_pk_mul_f32 v[128:129], v[128:129], v[128:129]
	v_fmac_f32_e32 v50, v67, v67
	v_mov_b32_e32 v136, v64
	v_mov_b32_e32 v137, v122
	v_add_f32_e32 v50, v129, v50
	v_pk_mul_f32 v[136:137], v[136:137], v[136:137]
	v_add_f32_e32 v50, v128, v50
	v_mov_b32_e32 v134, v120
	v_mov_b32_e32 v135, v70
	v_add_f32_e32 v50, v137, v50
	v_pk_mul_f32 v[134:135], v[134:135], v[134:135]
	v_add_f32_e32 v50, v136, v50
	v_mov_b32_e32 v132, v66
	v_mov_b32_e32 v133, v118
	v_add_f32_e32 v50, v135, v50
	v_pk_mul_f32 v[132:133], v[132:133], v[132:133]
	v_add_f32_e32 v50, v134, v50
	v_mov_b32_e32 v130, v116
	v_mov_b32_e32 v131, v52
	v_add_f32_e32 v50, v133, v50
	v_pk_mul_f32 v[130:131], v[130:131], v[130:131]
	v_add_f32_e32 v50, v132, v50
	v_add_f32_e32 v50, v131, v50
	v_add_f32_e32 v55, v130, v50
	ds_bpermute_b32 v76, v177, v55
	v_mov_b32_e32 v145, v38
	v_mov_b32_e32 v38, v51
	s_waitcnt vmcnt(9)
; __device__ __forceinline__ unsigned pk2(float lo, float hi) { unsigned r; asm("v_cvt_pk_bf16_f32 %0, %1, %2" : "=v"(r) : "v"(lo), "v"(hi)); return r; }
; __device__ __forceinline__ void attn_phase(const Params& P, LAS unsigned char* lds) {
;     ...
;                 for (int i = 0; i < 8; ++i) ss += yq[ks][i] * yq[ks][i]; }
;             ss += __shfl_xor(ss, 32);
;             const float rs = rsqrtf(ss * (1.f / 64.f) + 1e-6f) * 0.125f;
; #pragma unroll
;             for (int ks = 0; ks < 4; ++ks) { const f32x4 g0 = *(const f32x4*)(P.q_gain + 16 * ks + 8 * half), g1 = *(const f32x4*)(P.q_gain + 16 * ks + 8 * half + 4);
; #pragma unroll
;                 for (int i = 0; i < 4; ++i) { yq[ks][i] *= rs * g0[i]; yq[ks][4 + i] *= rs * g1[i]; } }
;             const float2* cr = rope + (tok >> 6) * 16 + 8 * half; const float2* cc = rope + (tok & 63) * 16 + 8 * half;
; #pragma unroll
;             for (int i = 0; i < 8; ++i) { const float2 tr = cr[i], tc = cc[i];
;                 const float a1 = yq[0][i], a2 = yq[1][i]; yq[0][i] = a1 * tr.x - a2 * tr.y; yq[1][i] = a1 * tr.y + a2 * tr.x;
;                 const float b1 = yq[2][i], b2 = yq[3][i]; yq[2][i] = b1 * tc.x - b2 * tc.y; yq[3][i] = b1 * tc.y + b2 * tc.x; }
; #pragma unroll
;             for (int ks = 0; ks < 4; ++ks) { union { bf16x8 v; unsigned u[4]; } pk;
; #pragma unroll
;                 for (int i = 0; i < 4; ++i) pk.u[i] = pk2(yq[ks][2 * i], yq[ks][2 * i + 1]);
;                 qf[ks] = pk.v; }
;         }
;         float m = P.sink[h], l = (half == 0) ? 1.f : 0.f;
;     ...
;         for (int ci = 0; ci < 5; ++ci) { const int cb = qb - 2 + ci; if (cb >= 0 && cb < SEQ / 64) attn_stage(lds + ci * KSZ, lds + VBASE + ci * VSZ, qk, Vt, 64 * cb, g, tid, P.k_gain, rope, true); }
	v_mov_b32_e32 v51, v44
	s_waitcnt vmcnt(8)
	v_mov_b32_e32 v50, v48
	s_waitcnt lgkmcnt(0)
	v_add_f32_e32 v44, v55, v76
	v_fmamk_f32 v44, v44, 0x3c800000, v197
	v_mul_f32_e32 v48, 0x4b800000, v44
	v_cmp_gt_f32_e32 vcc, s2, v44
	s_mov_b32 s2, 0x8200
	s_nop 0
	v_cndmask_b32_e32 v44, v44, v48, vcc
	v_rsq_f32_e32 v55, v44
	v_mov_b32_e32 v44, v49
	v_mov_b32_e32 v49, v42
	v_mov_b32_e32 v48, v46
	v_mul_f32_e32 v42, 0x45800000, v55
	v_cndmask_b32_e32 v42, v55, v42, vcc
	v_mul_f32_e32 v46, 0x3e000000, v42
	v_pk_mul_f32 v[48:49], v[48:49], v[46:47] op_sel_hi:[1,0]
	v_mov_b32_e32 v42, v47
	v_pk_mul_f32 v[48:49], v[48:49], v[154:155]
	v_pk_mul_f32 v[30:31], v[30:31], v[46:47] op_sel_hi:[1,0]
	v_pk_mul_f32 v[76:77], v[144:145], v[46:47] op_sel_hi:[1,0]
	v_pk_mul_f32 v[42:43], v[42:43], v[46:47] op_sel_hi:[1,0]
	v_pk_mul_f32 v[38:39], v[38:39], v[46:47] op_sel_hi:[1,0]
	v_pk_mul_f32 v[50:51], v[50:51], v[46:47] op_sel_hi:[1,0]
	v_pk_mul_f32 v[56:57], v[56:57], v[46:47] op_sel_hi:[1,0]
	v_pk_mul_f32 v[44:45], v[44:45], v[46:47] op_sel_hi:[1,0]
	v_pk_mul_f32 v[40:41], v[40:41], v[46:47] op_sel_hi:[1,0]
	v_pk_mul_f32 v[58:59], v[58:59], v[46:47] op_sel_hi:[1,0]
	v_pk_mul_f32 v[62:63], v[62:63], v[46:47] op_sel_hi:[1,0]
	v_pk_mul_f32 v[30:31], v[30:31], v[64:65]
	v_pk_mul_f32 v[26:27], v[26:27], v[46:47] op_sel_hi:[1,0]
	v_pk_mul_f32 v[60:61], v[60:61], v[46:47] op_sel_hi:[1,0]
	v_pk_mul_f32 v[64:65], v[80:81], v[46:47] op_sel_hi:[1,0]
	v_pk_mul_f32 v[32:33], v[32:33], v[46:47] op_sel_hi:[1,0]
	v_pk_mul_f32 v[28:29], v[28:29], v[46:47] op_sel_hi:[1,0]
	s_waitcnt vmcnt(0)
	v_pk_mul_f32 v[46:47], v[112:113], v[48:49] op_sel:[0,1] op_sel_hi:[1,0]
	v_pk_mul_f32 v[58:59], v[58:59], v[122:123]
	v_pk_mul_f32 v[52:53], v[64:65], v[52:53]
	v_sub_f32_e32 v64, v46, v47
	v_pk_mul_f32 v[46:47], v[112:113], v[48:49]
	v_pk_mul_f32 v[42:43], v[42:43], v[72:73]
	v_add_f32_e32 v48, v47, v46
	v_pk_mul_f32 v[46:47], v[14:15], v[58:59] op_sel:[0,1] op_sel_hi:[1,0]
	v_pk_mul_f32 v[14:15], v[14:15], v[58:59]
	v_sub_f32_e32 v46, v46, v47
	v_add_f32_e32 v47, v15, v14
	v_pk_mul_f32 v[14:15], v[114:115], v[42:43] op_sel:[0,1] op_sel_hi:[1,0]
	v_ashrrev_i32_e32 v55, 31, v54
	v_sub_f32_e32 v49, v14, v15
	v_pk_mul_f32 v[14:15], v[114:115], v[42:43]
	v_lshl_add_u64 v[42:43], v[54:55], 2, s[84:85]
	v_pk_mul_f32 v[62:63], v[62:63], v[118:119]
	global_load_dword v118, v[42:43], off
	v_add_f32_e32 v42, v15, v14
	v_pk_mul_f32 v[14:15], v[16:17], v[30:31] op_sel:[0,1] op_sel_hi:[1,0]
	v_pk_mul_f32 v[50:51], v[50:51], v[146:147]
	v_sub_f32_e32 v43, v14, v15
	v_pk_mul_f32 v[14:15], v[16:17], v[30:31]
	v_pk_mul_f32 v[60:61], v[60:61], v[70:71]
	v_add_f32_e32 v16, v15, v14
	v_pk_mul_f32 v[14:15], v[34:35], v[50:51] op_sel:[0,1] op_sel_hi:[1,0]
	v_pk_mul_f32 v[44:45], v[44:45], v[150:151]
	v_sub_f32_e32 v17, v14, v15
	v_pk_mul_f32 v[14:15], v[34:35], v[50:51]
	v_pk_mul_f32 v[32:33], v[32:33], v[120:121]
	v_add_f32_e32 v30, v15, v14
	v_pk_mul_f32 v[14:15], v[10:11], v[60:61] op_sel:[0,1] op_sel_hi:[1,0]
	v_pk_mul_f32 v[10:11], v[10:11], v[60:61]
	v_sub_f32_e32 v14, v14, v15
	v_add_f32_e32 v15, v11, v10
	v_pk_mul_f32 v[10:11], v[36:37], v[44:45] op_sel:[0,1] op_sel_hi:[1,0]
	v_pk_mul_f32 v[76:77], v[76:77], v[126:127]
	v_sub_f32_e32 v31, v10, v11
	v_pk_mul_f32 v[10:11], v[36:37], v[44:45]
	v_pk_mul_f32 v[38:39], v[38:39], v[74:75]
	v_add_f32_e32 v34, v11, v10
	v_pk_mul_f32 v[10:11], v[12:13], v[32:33] op_sel:[0,1] op_sel_hi:[1,0]
	v_pk_mul_f32 v[26:27], v[26:27], v[66:67]
	v_sub_f32_e32 v35, v10, v11
	v_pk_mul_f32 v[10:11], v[12:13], v[32:33]
	v_pk_mul_f32 v[56:57], v[56:57], v[68:69]
	v_add_f32_e32 v12, v11, v10
	v_pk_mul_f32 v[10:11], v[22:23], v[76:77] op_sel:[0,1] op_sel_hi:[1,0]
	v_pk_mul_f32 v[40:41], v[40:41], v[124:125]
	v_sub_f32_e32 v13, v10, v11
	v_pk_mul_f32 v[10:11], v[22:23], v[76:77]
	v_pk_mul_f32 v[28:29], v[28:29], v[116:117]
	v_add_f32_e32 v22, v11, v10
	v_pk_mul_f32 v[10:11], v[6:7], v[62:63] op_sel:[0,1] op_sel_hi:[1,0]
	v_pk_mul_f32 v[6:7], v[6:7], v[62:63]
	v_sub_f32_e32 v10, v10, v11
	v_add_f32_e32 v11, v7, v6
	v_pk_mul_f32 v[6:7], v[24:25], v[38:39] op_sel:[0,1] op_sel_hi:[1,0]
	v_cvt_pk_bf16_f32 v78, v64, v49
	v_cvt_pk_bf16_f32 v79, v17, v31
	v_cvt_pk_bf16_f32 v74, v48, v42
	v_cvt_pk_bf16_f32 v75, v30, v34
	v_cvt_pk_bf16_f32 v70, v46, v43
	s_nop 0
	v_sub_f32_e32 v23, v6, v7
	v_pk_mul_f32 v[6:7], v[24:25], v[38:39]
	v_cvt_pk_bf16_f32 v80, v13, v23
	v_cvt_pk_bf16_f32 v71, v14, v35
	v_cvt_pk_bf16_f32 v66, v47, v16
	v_cvt_pk_bf16_f32 v67, v15, v12
	s_nop 0
	v_add_f32_e32 v24, v7, v6
	v_pk_mul_f32 v[6:7], v[8:9], v[26:27] op_sel:[0,1] op_sel_hi:[1,0]
	v_cvt_pk_bf16_f32 v76, v22, v24
	s_nop 0
	v_sub_f32_e32 v25, v6, v7
	v_pk_mul_f32 v[6:7], v[8:9], v[26:27]
	v_cvt_pk_bf16_f32 v72, v10, v25
	s_nop 0
	v_add_f32_e32 v8, v7, v6
	v_pk_mul_f32 v[6:7], v[18:19], v[56:57] op_sel:[0,1] op_sel_hi:[1,0]
	v_cvt_pk_bf16_f32 v68, v11, v8
	s_nop 0
	v_sub_f32_e32 v9, v6, v7
	v_pk_mul_f32 v[6:7], v[18:19], v[56:57]
	s_nop 0
	v_add_f32_e32 v18, v7, v6
	v_pk_mul_f32 v[6:7], v[2:3], v[52:53] op_sel:[0,1] op_sel_hi:[1,0]
	v_pk_mul_f32 v[2:3], v[2:3], v[52:53]
	v_sub_f32_e32 v6, v6, v7
	v_add_f32_e32 v7, v3, v2
	v_pk_mul_f32 v[2:3], v[20:21], v[40:41] op_sel:[0,1] op_sel_hi:[1,0]
	s_nop 0
	v_sub_f32_e32 v19, v2, v3
	v_pk_mul_f32 v[2:3], v[20:21], v[40:41]
	v_cvt_pk_bf16_f32 v81, v9, v19
	s_nop 0
	v_add_f32_e32 v20, v3, v2
	v_pk_mul_f32 v[2:3], v[4:5], v[28:29] op_sel:[0,1] op_sel_hi:[1,0]
	v_cvt_pk_bf16_f32 v77, v18, v20
	s_nop 0
	v_sub_f32_e32 v21, v2, v3
	v_pk_mul_f32 v[2:3], v[4:5], v[28:29]
	v_cvt_pk_bf16_f32 v73, v6, v21
	v_lshlrev_b32_e32 v6, 1, v86
	v_add_f32_e32 v2, v3, v2
	v_cvt_pk_bf16_f32 v69, v7, v2
	v_add_u32_e32 v2, s35, v179
	v_mad_i64_i32 v[112:113], s[8:9], v2, s2, v[92:93]
	s_cselect_b64 s[8:9], -1, 0
	s_cmpk_gt_u32 s1, 0xff
	s_mov_b32 s2, 0x800000
	global_load_dwordx4 v[222:225], v[104:105], off offset:16
	global_load_dwordx4 v[226:229], v[104:105], off
	s_cbranch_scc1 .LBB0_726
; #define LAS __attribute__((address_space(3)))
; __device__ __forceinline__ unsigned pk2(float lo, float hi) { unsigned r; asm("v_cvt_pk_bf16_f32 %0, %1, %2" : "=v"(r) : "v"(lo), "v"(hi)); return r; }
; __device__ __forceinline__ float bflo(unsigned u) { return __uint_as_float(u << 16); }
; __device__ __forceinline__ void attn_stage(LAS unsigned char* Kl, LAS unsigned char* Vl, const bf16_t* qk, const bf16_t* Vt, int tok0, int g, int tid, const float* kgain, const float2* rope, bool do_rope) {
;     const int row = tid >> 3, piece = tid & 7;
;     const u32x4 kraw = *(const u32x4*)(qk + (size_t)(tok0 + row) * 1280 + 1024 + 64 * g + 8 * piece);
;     float y[8] = {bflo(kraw.x), bfhi(kraw.x), bflo(kraw.y), bfhi(kraw.y), bflo(kraw.z), bfhi(kraw.z), bflo(kraw.w), bfhi(kraw.w)};
;     float ss = 0.f;
; #pragma unroll
;     for (int i = 0; i < 8; ++i) ss += y[i] * y[i];
;     ss += __shfl_xor(ss, 1); ss += __shfl_xor(ss, 2); ss += __shfl_xor(ss, 4);
;     const float rs = rsqrtf(ss * (1.f / 64.f) + 1e-6f);
;     const f32x4 g0 = *(const f32x4*)(kgain + 8 * piece), g1 = *(const f32x4*)(kgain + 8 * piece + 4);
; #pragma unroll
;     for (int i = 0; i < 4; ++i) { y[i] *= rs * g0[i]; y[4 + i] *= rs * g1[i]; }
;     float py[8];
; #pragma unroll
;     for (int i = 0; i < 8; ++i) py[i] = __shfl_xor(y[i], 2);
;     if (do_rope) {
;         const int token = tok0 + row, pos = (piece < 4) ? (token >> 6) : (token & 63);
;         const float2* cs = rope + pos * 16 + 8 * (piece & 1);
; #pragma unroll
;         for (int i = 0; i < 8; ++i) { const float2 t = cs[i]; y[i] = (piece & 2) ? (py[i] * t.y + y[i] * t.x) : (y[i] * t.x - py[i] * t.y); }
;     }
;     u32x4 kv; kv.x = pk2(y[0], y[1]); kv.y = pk2(y[2], y[3]); kv.z = pk2(y[4], y[5]); kv.w = pk2(y[6], y[7]);
;     *(LAS u32x4*)(Kl + row * 144 + piece * 16) = kv;
;     const u32x4 vv = *(const u32x4*)(Vt + (size_t)(g * 64 + row) * MTOT + tok0 + 8 * piece);
;     LAS u32x2* vd = (LAS u32x2*)(Vl + row * 136 + piece * 16); vd[0] = (u32x2){vv.x, vv.y}; vd[1] = (u32x2){vv.z, vv.w};
; __device__ __forceinline__ void attn_phase(const Params& P, LAS unsigned char* lds) {
;     ...
;         for (int ci = 0; ci < 5; ++ci) { const int cb = qb - 2 + ci; if (cb >= 0 && cb < SEQ / 64) attn_stage(lds + ci * KSZ, lds + VBASE + ci * VSZ, qk, Vt, 64 * cb, g, tid, P.k_gain, rope, true); }
	v_lshl_add_u32 v20, s1, 6, v179
	v_mov_b64_e32 v[2:3], s[46:47]
	v_mad_i64_i32 v[2:3], s[14:15], v20, s3, v[2:3]
	v_readlane_b32 s14, v252, 30
	v_readlane_b32 s15, v252, 31
	s_lshl_b32 s14, s35, 1
	v_mov_b32_e32 v7, v1
	v_lshl_add_u64 v[2:3], v[2:3], 0, s[14:15]
	v_lshl_add_u64 v[2:3], v[2:3], 0, v[6:7]
	global_load_dwordx4 v[2:5], v[2:3], off offset:2048
	s_lshl_b32 s14, s1, 7
	s_mov_b32 s1, s15
	v_writelane_b32 v252, s0, 30
	v_ashrrev_i32_e32 v16, 6, v20
	v_cndmask_b32_e64 v16, v183, v16, s[38:39]
	v_lshlrev_b32_e32 v16, 4, v16
	v_ashrrev_i32_e32 v17, 31, v16
	v_lshl_add_u64 v[16:17], v[16:17], 3, v[88:89]
	global_load_dwordx4 v[230:233], v[16:17], off offset:48
	global_load_dwordx4 v[234:237], v[16:17], off offset:32
	global_load_dwordx4 v[238:241], v[16:17], off offset:16
	global_load_dwordx4 v[242:245], v[16:17], off
	v_lshl_add_u64 v[18:19], v[112:113], 0, s[14:15]
	global_load_dwordx2 v[246:247], v[18:19], off
	global_load_dwordx2 v[198:199], v[18:19], off offset:8
	s_waitcnt vmcnt(6)
	v_lshlrev_b32_e32 v12, 16, v2
	v_and_b32_e32 v13, 0xffff0000, v2
	v_pk_mul_f32 v[8:9], v[12:13], v[12:13]
	v_and_b32_e32 v14, 0xffff0000, v3
	v_lshlrev_b32_e32 v15, 16, v3
	v_pk_mul_f32 v[2:3], v[14:15], v[14:15]
	v_add_f32_e32 v7, v8, v9
	v_and_b32_e32 v16, 0xffff0000, v4
	v_lshlrev_b32_e32 v17, 16, v4
	v_add_f32_e32 v3, v3, v7
	v_pk_mul_f32 v[10:11], v[16:17], v[16:17]
	v_add_f32_e32 v2, v2, v3
	v_and_b32_e32 v18, 0xffff0000, v5
	v_lshlrev_b32_e32 v19, 16, v5
	v_add_f32_e32 v2, v11, v2
	v_pk_mul_f32 v[4:5], v[18:19], v[18:19]
	v_add_f32_e32 v2, v10, v2
	v_add_f32_e32 v2, v5, v2
	v_add_f32_e32 v2, v4, v2
	ds_bpermute_b32 v3, v180, v2
	v_writelane_b32 v252, s1, 31
	s_waitcnt lgkmcnt(0)
	v_add_f32_e32 v2, v2, v3
	ds_bpermute_b32 v3, v181, v2
	s_waitcnt lgkmcnt(0)
	v_add_f32_e32 v2, v2, v3
	ds_bpermute_b32 v3, v182, v2
	s_waitcnt lgkmcnt(0)
	v_add_f32_e32 v2, v2, v3
	v_fmamk_f32 v2, v2, 0x3c800000, v197
	v_cmp_gt_f32_e32 vcc, s2, v2
	v_mul_f32_e32 v3, 0x4b800000, v2
	s_nop 0
	v_cndmask_b32_e32 v2, v2, v3, vcc
	v_rsq_f32_e32 v2, v2
	s_nop 0
	v_mul_f32_e32 v3, 0x45800000, v2
	v_cndmask_b32_e32 v7, v2, v3, vcc
	v_mov_b64_e32 v[2:3], v[222:223]
	v_mov_b64_e32 v[4:5], v[224:225]
	v_mov_b64_e32 v[8:9], v[226:227]
	v_mov_b64_e32 v[10:11], v[228:229]
	s_waitcnt vmcnt(1)
	v_mul_f32_e32 v2, v2, v7
	v_mul_f32_e32 v22, v2, v17
	s_waitcnt vmcnt(0)
	v_mul_f32_e32 v2, v9, v7
	v_mul_f32_e32 v23, v2, v13
	v_mul_f32_e32 v2, v3, v7
	v_mul_f32_e32 v24, v2, v16
	v_mul_f32_e32 v2, v10, v7
	v_mul_f32_e32 v25, v2, v15
	v_mul_f32_e32 v2, v4, v7
	v_mul_f32_e32 v26, v2, v19
	v_mul_f32_e32 v2, v11, v7
	v_mul_f32_e32 v27, v2, v14
	v_mul_f32_e32 v2, v5, v7
	v_mul_f32_e32 v8, v8, v7
	v_mul_f32_e32 v7, v2, v18
	v_ashrrev_i32_e32 v2, 6, v20
	v_cndmask_b32_e64 v2, v183, v2, s[38:39]
	v_lshlrev_b32_e32 v2, 4, v2
	v_ashrrev_i32_e32 v3, 31, v2
	v_lshl_add_u64 v[16:17], v[2:3], 3, v[88:89]
	v_mul_f32_e32 v21, v8, v12
	s_waitcnt vmcnt(2)
	v_mov_b64_e32 v[2:3], v[230:231]
	v_mov_b64_e32 v[4:5], v[232:233]
	v_mov_b64_e32 v[8:9], v[234:235]
	v_mov_b64_e32 v[10:11], v[236:237]
	v_mov_b64_e32 v[12:13], v[238:239]
	v_mov_b64_e32 v[14:15], v[240:241]
	s_nop 0
	v_mov_b64_e32 v[16:17], v[242:243]
	v_mov_b64_e32 v[18:19], v[244:245]
	ds_bpermute_b32 v32, v181, v22
	ds_bpermute_b32 v33, v181, v24
	ds_bpermute_b32 v28, v181, v21
	ds_bpermute_b32 v30, v181, v25
	ds_bpermute_b32 v34, v181, v26
	ds_bpermute_b32 v29, v181, v23
	ds_bpermute_b32 v31, v181, v27
	ds_bpermute_b32 v35, v181, v7
	s_waitcnt vmcnt(3) lgkmcnt(3)
	v_mul_f32_e32 v3, v3, v34
	s_waitcnt vmcnt(2)
	v_mul_f32_e32 v9, v9, v32
	v_cndmask_b32_e64 v9, v9, -v9, s[40:41]
	v_fmac_f32_e32 v9, v8, v22
	v_mul_f32_e32 v8, v11, v33
	s_waitcnt vmcnt(0)
	v_mul_f32_e32 v17, v17, v28
	v_mul_f32_e32 v13, v13, v30
	v_cndmask_b32_e64 v8, v8, -v8, s[40:41]
	v_cndmask_b32_e64 v17, v17, -v17, s[40:41]
	v_cndmask_b32_e64 v13, v13, -v13, s[40:41]
	v_fmac_f32_e32 v8, v10, v24
	v_cndmask_b32_e64 v10, v3, -v3, s[40:41]
	v_fmac_f32_e32 v17, v16, v21
	s_waitcnt lgkmcnt(2)
	v_mul_f32_e32 v16, v19, v29
	v_fmac_f32_e32 v13, v12, v25
	s_waitcnt lgkmcnt(1)
	v_mul_f32_e32 v12, v15, v31
	v_fmac_f32_e32 v10, v26, v2
	s_waitcnt lgkmcnt(0)
	v_mul_f32_e32 v2, v5, v35
	v_cndmask_b32_e64 v16, v16, -v16, s[40:41]
	v_cndmask_b32_e64 v12, v12, -v12, s[40:41]
	v_cndmask_b32_e64 v5, v2, -v2, s[40:41]
	v_fmac_f32_e32 v16, v18, v23
	v_fmac_f32_e32 v12, v14, v27
	v_fmac_f32_e32 v5, v7, v4
	v_cvt_pk_bf16_f32 v2, v17, v16
	v_cvt_pk_bf16_f32 v3, v13, v12
	v_cvt_pk_bf16_f32 v4, v9, v8
	v_cvt_pk_bf16_f32 v5, v10, v5
	ds_write_b128 v107, v[2:5]
	s_nop 0
	s_nop 0
	s_waitcnt vmcnt(0)
	ds_write2_b64 v186, v[246:247], v[198:199] offset1:1
; #define LAS __attribute__((address_space(3)))
; __device__ __forceinline__ unsigned pk2(float lo, float hi) { unsigned r; asm("v_cvt_pk_bf16_f32 %0, %1, %2" : "=v"(r) : "v"(lo), "v"(hi)); return r; }
; __device__ __forceinline__ float bflo(unsigned u) { return __uint_as_float(u << 16); }
; __device__ __forceinline__ void attn_stage(LAS unsigned char* Kl, LAS unsigned char* Vl, const bf16_t* qk, const bf16_t* Vt, int tok0, int g, int tid, const float* kgain, const float2* rope, bool do_rope) {
;     const int row = tid >> 3, piece = tid & 7;
;     const u32x4 kraw = *(const u32x4*)(qk + (size_t)(tok0 + row) * 1280 + 1024 + 64 * g + 8 * piece);
;     float y[8] = {bflo(kraw.x), bfhi(kraw.x), bflo(kraw.y), bfhi(kraw.y), bflo(kraw.z), bfhi(kraw.z), bflo(kraw.w), bfhi(kraw.w)};
;     float ss = 0.f;
; #pragma unroll
;     for (int i = 0; i < 8; ++i) ss += y[i] * y[i];
;     ss += __shfl_xor(ss, 1); ss += __shfl_xor(ss, 2); ss += __shfl_xor(ss, 4);
;     const float rs = rsqrtf(ss * (1.f / 64.f) + 1e-6f);
;     const f32x4 g0 = *(const f32x4*)(kgain + 8 * piece), g1 = *(const f32x4*)(kgain + 8 * piece + 4);
; #pragma unroll
;     for (int i = 0; i < 4; ++i) { y[i] *= rs * g0[i]; y[4 + i] *= rs * g1[i]; }
;     float py[8];
; #pragma unroll
;     for (int i = 0; i < 8; ++i) py[i] = __shfl_xor(y[i], 2);
;     if (do_rope) {
;         const int token = tok0 + row, pos = (piece < 4) ? (token >> 6) : (token & 63);
;         const float2* cs = rope + pos * 16 + 8 * (piece & 1);
; #pragma unroll
;         for (int i = 0; i < 8; ++i) { const float2 t = cs[i]; y[i] = (piece & 2) ? (py[i] * t.y + y[i] * t.x) : (y[i] * t.x - py[i] * t.y); }
;     }
;     u32x4 kv; kv.x = pk2(y[0], y[1]); kv.y = pk2(y[2], y[3]); kv.z = pk2(y[4], y[5]); kv.w = pk2(y[6], y[7]);
;     *(LAS u32x4*)(Kl + row * 144 + piece * 16) = kv;
;     const u32x4 vv = *(const u32x4*)(Vt + (size_t)(g * 64 + row) * MTOT + tok0 + 8 * piece);
;     LAS u32x2* vd = (LAS u32x2*)(Vl + row * 136 + piece * 16); vd[0] = (u32x2){vv.x, vv.y}; vd[1] = (u32x2){vv.z, vv.w};
; __device__ __forceinline__ void attn_phase(const Params& P, LAS unsigned char* lds) {
;     ...
;         for (int ci = 0; ci < 5; ++ci) { const int cb = qb - 2 + ci; if (cb >= 0 && cb < SEQ / 64) attn_stage(lds + ci * KSZ, lds + VBASE + ci * VSZ, qk, Vt, 64 * cb, g, tid, P.k_gain, rope, true); }
.LBB0_726:
	s_add_i32 s1, s18, -1
	s_cmpk_lt_u32 s1, 0x100
	s_cselect_b64 s[16:17], -1, 0
	s_cmpk_gt_u32 s1, 0xff
	v_add_u32_e32 v114, 0xd600, v185
	s_cbranch_scc1 .LBB0_728
	v_lshl_add_u32 v20, s1, 6, v179
	v_mov_b64_e32 v[2:3], s[46:47]
	v_mad_i64_i32 v[2:3], s[14:15], v20, s3, v[2:3]
	v_readlane_b32 s14, v252, 30
	v_readlane_b32 s15, v252, 31
	s_lshl_b32 s14, s35, 1
	v_mov_b32_e32 v7, v1
	v_lshl_add_u64 v[2:3], v[2:3], 0, s[14:15]
	v_lshl_add_u64 v[2:3], v[2:3], 0, v[6:7]
	global_load_dwordx4 v[2:5], v[2:3], off offset:2048
	s_lshl_b32 s14, s1, 7
	s_mov_b32 s1, s15
	v_writelane_b32 v252, s0, 30
	v_ashrrev_i32_e32 v16, 6, v20
	v_cndmask_b32_e64 v16, v183, v16, s[38:39]
	v_lshlrev_b32_e32 v16, 4, v16
	v_ashrrev_i32_e32 v17, 31, v16
	v_lshl_add_u64 v[16:17], v[16:17], 3, v[88:89]
	global_load_dwordx4 v[230:233], v[16:17], off offset:48
	global_load_dwordx4 v[234:237], v[16:17], off offset:32
	global_load_dwordx4 v[238:241], v[16:17], off offset:16
	global_load_dwordx4 v[242:245], v[16:17], off
	v_lshl_add_u64 v[18:19], v[112:113], 0, s[14:15]
	global_load_dwordx2 v[246:247], v[18:19], off
	global_load_dwordx2 v[198:199], v[18:19], off offset:8
	s_waitcnt vmcnt(6)
	v_lshlrev_b32_e32 v12, 16, v2
	v_and_b32_e32 v13, 0xffff0000, v2
	v_pk_mul_f32 v[8:9], v[12:13], v[12:13]
	v_and_b32_e32 v14, 0xffff0000, v3
	v_lshlrev_b32_e32 v15, 16, v3
	v_pk_mul_f32 v[2:3], v[14:15], v[14:15]
	v_add_f32_e32 v7, v8, v9
	v_and_b32_e32 v16, 0xffff0000, v4
	v_lshlrev_b32_e32 v17, 16, v4
	v_add_f32_e32 v3, v3, v7
	v_pk_mul_f32 v[10:11], v[16:17], v[16:17]
	v_add_f32_e32 v2, v2, v3
	v_and_b32_e32 v18, 0xffff0000, v5
	v_lshlrev_b32_e32 v19, 16, v5
	v_add_f32_e32 v2, v11, v2
	v_pk_mul_f32 v[4:5], v[18:19], v[18:19]
	v_add_f32_e32 v2, v10, v2
	v_add_f32_e32 v2, v5, v2
	v_add_f32_e32 v2, v4, v2
	ds_bpermute_b32 v3, v180, v2
	v_writelane_b32 v252, s1, 31
	s_waitcnt lgkmcnt(0)
	v_add_f32_e32 v2, v2, v3
	ds_bpermute_b32 v3, v181, v2
	s_waitcnt lgkmcnt(0)
	v_add_f32_e32 v2, v2, v3
	ds_bpermute_b32 v3, v182, v2
	s_waitcnt lgkmcnt(0)
	v_add_f32_e32 v2, v2, v3
	v_fmamk_f32 v2, v2, 0x3c800000, v197
	v_cmp_gt_f32_e32 vcc, s2, v2
	v_mul_f32_e32 v3, 0x4b800000, v2
	s_nop 0
	v_cndmask_b32_e32 v2, v2, v3, vcc
	v_rsq_f32_e32 v2, v2
	s_nop 0
	v_mul_f32_e32 v3, 0x45800000, v2
	v_cndmask_b32_e32 v7, v2, v3, vcc
	v_mov_b64_e32 v[2:3], v[222:223]
	v_mov_b64_e32 v[4:5], v[224:225]
	v_mov_b64_e32 v[8:9], v[226:227]
	v_mov_b64_e32 v[10:11], v[228:229]
	s_waitcnt vmcnt(1)
	v_mul_f32_e32 v2, v2, v7
	v_mul_f32_e32 v22, v2, v17
	s_waitcnt vmcnt(0)
	v_mul_f32_e32 v2, v9, v7
	v_mul_f32_e32 v23, v2, v13
	v_mul_f32_e32 v2, v3, v7
	v_mul_f32_e32 v24, v2, v16
	v_mul_f32_e32 v2, v10, v7
	v_mul_f32_e32 v25, v2, v15
	v_mul_f32_e32 v2, v4, v7
	v_mul_f32_e32 v26, v2, v19
	v_mul_f32_e32 v2, v11, v7
	v_mul_f32_e32 v27, v2, v14
	v_mul_f32_e32 v2, v5, v7
	v_mul_f32_e32 v8, v8, v7
	v_mul_f32_e32 v7, v2, v18
	v_ashrrev_i32_e32 v2, 6, v20
	v_cndmask_b32_e64 v2, v183, v2, s[38:39]
	v_lshlrev_b32_e32 v2, 4, v2
	v_ashrrev_i32_e32 v3, 31, v2
	v_lshl_add_u64 v[16:17], v[2:3], 3, v[88:89]
	v_mul_f32_e32 v21, v8, v12
	s_waitcnt vmcnt(2)
	v_mov_b64_e32 v[2:3], v[230:231]
	v_mov_b64_e32 v[4:5], v[232:233]
	v_mov_b64_e32 v[8:9], v[234:235]
	v_mov_b64_e32 v[10:11], v[236:237]
	v_mov_b64_e32 v[12:13], v[238:239]
	v_mov_b64_e32 v[14:15], v[240:241]
	s_nop 0
	v_mov_b64_e32 v[16:17], v[242:243]
	v_mov_b64_e32 v[18:19], v[244:245]
	ds_bpermute_b32 v32, v181, v22
	ds_bpermute_b32 v33, v181, v24
	ds_bpermute_b32 v28, v181, v21
	ds_bpermute_b32 v30, v181, v25
	ds_bpermute_b32 v34, v181, v26
	ds_bpermute_b32 v29, v181, v23
	ds_bpermute_b32 v31, v181, v27
	ds_bpermute_b32 v35, v181, v7
	s_waitcnt vmcnt(3) lgkmcnt(3)
	v_mul_f32_e32 v3, v3, v34
	s_waitcnt vmcnt(2)
	v_mul_f32_e32 v9, v9, v32
	v_cndmask_b32_e64 v9, v9, -v9, s[40:41]
	v_fmac_f32_e32 v9, v8, v22
	v_mul_f32_e32 v8, v11, v33
	s_waitcnt vmcnt(0)
	v_mul_f32_e32 v17, v17, v28
	v_mul_f32_e32 v13, v13, v30
	v_cndmask_b32_e64 v8, v8, -v8, s[40:41]
	v_cndmask_b32_e64 v17, v17, -v17, s[40:41]
	v_cndmask_b32_e64 v13, v13, -v13, s[40:41]
	v_fmac_f32_e32 v8, v10, v24
	v_cndmask_b32_e64 v10, v3, -v3, s[40:41]
	v_fmac_f32_e32 v17, v16, v21
	s_waitcnt lgkmcnt(2)
	v_mul_f32_e32 v16, v19, v29
	v_fmac_f32_e32 v13, v12, v25
	s_waitcnt lgkmcnt(1)
	v_mul_f32_e32 v12, v15, v31
	v_fmac_f32_e32 v10, v26, v2
	s_waitcnt lgkmcnt(0)
	v_mul_f32_e32 v2, v5, v35
	v_cndmask_b32_e64 v16, v16, -v16, s[40:41]
	v_cndmask_b32_e64 v12, v12, -v12, s[40:41]
	v_cndmask_b32_e64 v5, v2, -v2, s[40:41]
	v_fmac_f32_e32 v16, v18, v23
	v_fmac_f32_e32 v12, v14, v27
	v_fmac_f32_e32 v5, v7, v4
	v_cvt_pk_bf16_f32 v2, v17, v16
	v_cvt_pk_bf16_f32 v3, v13, v12
	v_cvt_pk_bf16_f32 v4, v9, v8
	v_cvt_pk_bf16_f32 v5, v10, v5
	ds_write_b128 v107, v[2:5] offset:9216
	s_nop 0
	s_nop 0
	s_waitcnt vmcnt(0)
	ds_write2_b64 v114, v[246:247], v[198:199] offset1:1
; #define LAS __attribute__((address_space(3)))
; __device__ __forceinline__ unsigned pk2(float lo, float hi) { unsigned r; asm("v_cvt_pk_bf16_f32 %0, %1, %2" : "=v"(r) : "v"(lo), "v"(hi)); return r; }
; __device__ __forceinline__ float bflo(unsigned u) { return __uint_as_float(u << 16); }
; __device__ __forceinline__ void attn_stage(LAS unsigned char* Kl, LAS unsigned char* Vl, const bf16_t* qk, const bf16_t* Vt, int tok0, int g, int tid, const float* kgain, const float2* rope, bool do_rope) {
;     const int row = tid >> 3, piece = tid & 7;
;     const u32x4 kraw = *(const u32x4*)(qk + (size_t)(tok0 + row) * 1280 + 1024 + 64 * g + 8 * piece);
;     float y[8] = {bflo(kraw.x), bfhi(kraw.x), bflo(kraw.y), bfhi(kraw.y), bflo(kraw.z), bfhi(kraw.z), bflo(kraw.w), bfhi(kraw.w)};
;     float ss = 0.f;
; #pragma unroll
;     for (int i = 0; i < 8; ++i) ss += y[i] * y[i];
;     ss += __shfl_xor(ss, 1); ss += __shfl_xor(ss, 2); ss += __shfl_xor(ss, 4);
;     const float rs = rsqrtf(ss * (1.f / 64.f) + 1e-6f);
;     const f32x4 g0 = *(const f32x4*)(kgain + 8 * piece), g1 = *(const f32x4*)(kgain + 8 * piece + 4);
; #pragma unroll
;     for (int i = 0; i < 4; ++i) { y[i] *= rs * g0[i]; y[4 + i] *= rs * g1[i]; }
;     float py[8];
; #pragma unroll
;     for (int i = 0; i < 8; ++i) py[i] = __shfl_xor(y[i], 2);
;     if (do_rope) {
;         const int token = tok0 + row, pos = (piece < 4) ? (token >> 6) : (token & 63);
;         const float2* cs = rope + pos * 16 + 8 * (piece & 1);
; #pragma unroll
;         for (int i = 0; i < 8; ++i) { const float2 t = cs[i]; y[i] = (piece & 2) ? (py[i] * t.y + y[i] * t.x) : (y[i] * t.x - py[i] * t.y); }
;     }
;     u32x4 kv; kv.x = pk2(y[0], y[1]); kv.y = pk2(y[2], y[3]); kv.z = pk2(y[4], y[5]); kv.w = pk2(y[6], y[7]);
;     *(LAS u32x4*)(Kl + row * 144 + piece * 16) = kv;
;     const u32x4 vv = *(const u32x4*)(Vt + (size_t)(g * 64 + row) * MTOT + tok0 + 8 * piece);
;     LAS u32x2* vd = (LAS u32x2*)(Vl + row * 136 + piece * 16); vd[0] = (u32x2){vv.x, vv.y}; vd[1] = (u32x2){vv.z, vv.w};
; __device__ __forceinline__ void attn_phase(const Params& P, LAS unsigned char* lds) {
;     ...
;         for (int ci = 0; ci < 5; ++ci) { const int cb = qb - 2 + ci; if (cb >= 0 && cb < SEQ / 64) attn_stage(lds + ci * KSZ, lds + VBASE + ci * VSZ, qk, Vt, 64 * cb, g, tid, P.k_gain, rope, true); }
.LBB0_728:
	s_cmpk_lt_u32 s18, 0x100
	s_cselect_b64 s[14:15], -1, 0
	s_cmpk_gt_u32 s18, 0xff
	v_add_u32_e32 v116, 0xf800, v185
	s_cbranch_scc1 .LBB0_730
	v_add_u32_e32 v20, s0, v179
	v_mov_b64_e32 v[2:3], s[46:47]
	v_mad_i64_i32 v[2:3], s[36:37], v20, s3, v[2:3]
	v_readlane_b32 s36, v252, 30
	v_readlane_b32 s37, v252, 31
	s_lshl_b32 s36, s35, 1
	v_mov_b32_e32 v7, v1
	v_lshl_add_u64 v[2:3], v[2:3], 0, s[36:37]
	v_lshl_add_u64 v[2:3], v[2:3], 0, v[6:7]
	global_load_dwordx4 v[2:5], v[2:3], off offset:2048
	s_mov_b32 s1, s37
	v_writelane_b32 v252, s0, 30
	v_ashrrev_i32_e32 v16, 6, v20
	v_cndmask_b32_e64 v16, v183, v16, s[38:39]
	v_lshlrev_b32_e32 v16, 4, v16
	v_ashrrev_i32_e32 v17, 31, v16
	v_lshl_add_u64 v[16:17], v[16:17], 3, v[88:89]
	global_load_dwordx4 v[230:233], v[16:17], off offset:48
	global_load_dwordx4 v[234:237], v[16:17], off offset:32
	global_load_dwordx4 v[238:241], v[16:17], off offset:16
	global_load_dwordx4 v[242:245], v[16:17], off
	v_lshl_add_u64 v[18:19], s[0:1], 1, v[112:113]
	global_load_dwordx2 v[246:247], v[18:19], off
	global_load_dwordx2 v[198:199], v[18:19], off offset:8
	s_waitcnt vmcnt(6)
	v_lshlrev_b32_e32 v12, 16, v2
	v_and_b32_e32 v13, 0xffff0000, v2
	v_pk_mul_f32 v[8:9], v[12:13], v[12:13]
	v_and_b32_e32 v14, 0xffff0000, v3
	v_lshlrev_b32_e32 v15, 16, v3
	v_pk_mul_f32 v[2:3], v[14:15], v[14:15]
	v_add_f32_e32 v7, v8, v9
	v_and_b32_e32 v16, 0xffff0000, v4
	v_lshlrev_b32_e32 v17, 16, v4
	v_add_f32_e32 v3, v3, v7
	v_pk_mul_f32 v[10:11], v[16:17], v[16:17]
	v_add_f32_e32 v2, v2, v3
	v_and_b32_e32 v18, 0xffff0000, v5
	v_lshlrev_b32_e32 v19, 16, v5
	v_add_f32_e32 v2, v11, v2
	v_pk_mul_f32 v[4:5], v[18:19], v[18:19]
	v_add_f32_e32 v2, v10, v2
	v_add_f32_e32 v2, v5, v2
	v_add_f32_e32 v2, v4, v2
	ds_bpermute_b32 v3, v180, v2
	v_writelane_b32 v252, s1, 31
	s_mov_b32 s1, s37
	s_waitcnt lgkmcnt(0)
	v_add_f32_e32 v2, v2, v3
	ds_bpermute_b32 v3, v181, v2
	s_waitcnt lgkmcnt(0)
	v_add_f32_e32 v2, v2, v3
	ds_bpermute_b32 v3, v182, v2
	s_waitcnt lgkmcnt(0)
	v_add_f32_e32 v2, v2, v3
	v_fmamk_f32 v2, v2, 0x3c800000, v197
	v_cmp_gt_f32_e32 vcc, s2, v2
	v_mul_f32_e32 v3, 0x4b800000, v2
	s_nop 0
	v_cndmask_b32_e32 v2, v2, v3, vcc
	v_rsq_f32_e32 v2, v2
	s_nop 0
	v_mul_f32_e32 v3, 0x45800000, v2
	v_cndmask_b32_e32 v7, v2, v3, vcc
	v_mov_b64_e32 v[2:3], v[222:223]
	v_mov_b64_e32 v[4:5], v[224:225]
	v_mov_b64_e32 v[8:9], v[226:227]
	v_mov_b64_e32 v[10:11], v[228:229]
	s_waitcnt vmcnt(1)
	v_mul_f32_e32 v2, v2, v7
	v_mul_f32_e32 v22, v2, v17
	s_waitcnt vmcnt(0)
	v_mul_f32_e32 v2, v9, v7
	v_mul_f32_e32 v23, v2, v13
	v_mul_f32_e32 v2, v3, v7
	v_mul_f32_e32 v24, v2, v16
	v_mul_f32_e32 v2, v10, v7
	v_mul_f32_e32 v25, v2, v15
	v_mul_f32_e32 v2, v4, v7
	v_mul_f32_e32 v26, v2, v19
	v_mul_f32_e32 v2, v11, v7
	v_mul_f32_e32 v27, v2, v14
	v_mul_f32_e32 v2, v5, v7
	v_mul_f32_e32 v8, v8, v7
	v_mul_f32_e32 v7, v2, v18
	v_ashrrev_i32_e32 v2, 6, v20
	v_cndmask_b32_e64 v2, v183, v2, s[38:39]
	v_lshlrev_b32_e32 v2, 4, v2
	v_ashrrev_i32_e32 v3, 31, v2
	v_lshl_add_u64 v[16:17], v[2:3], 3, v[88:89]
	v_mul_f32_e32 v21, v8, v12
	s_waitcnt vmcnt(2)
	v_mov_b64_e32 v[2:3], v[230:231]
	v_mov_b64_e32 v[4:5], v[232:233]
	v_mov_b64_e32 v[8:9], v[234:235]
	v_mov_b64_e32 v[10:11], v[236:237]
	v_mov_b64_e32 v[12:13], v[238:239]
	v_mov_b64_e32 v[14:15], v[240:241]
	s_nop 0
	v_mov_b64_e32 v[16:17], v[242:243]
	v_mov_b64_e32 v[18:19], v[244:245]
	ds_bpermute_b32 v32, v181, v22
	ds_bpermute_b32 v33, v181, v24
	ds_bpermute_b32 v28, v181, v21
	ds_bpermute_b32 v30, v181, v25
	ds_bpermute_b32 v34, v181, v26
	ds_bpermute_b32 v29, v181, v23
	ds_bpermute_b32 v31, v181, v27
	ds_bpermute_b32 v35, v181, v7
	s_waitcnt vmcnt(3) lgkmcnt(3)
	v_mul_f32_e32 v3, v3, v34
	s_waitcnt vmcnt(2)
	v_mul_f32_e32 v9, v9, v32
	v_cndmask_b32_e64 v9, v9, -v9, s[40:41]
	v_fmac_f32_e32 v9, v8, v22
	v_mul_f32_e32 v8, v11, v33
	s_waitcnt vmcnt(0)
	v_mul_f32_e32 v17, v17, v28
	v_mul_f32_e32 v13, v13, v30
	v_cndmask_b32_e64 v8, v8, -v8, s[40:41]
	v_cndmask_b32_e64 v17, v17, -v17, s[40:41]
	v_cndmask_b32_e64 v13, v13, -v13, s[40:41]
	v_fmac_f32_e32 v8, v10, v24
	v_cndmask_b32_e64 v10, v3, -v3, s[40:41]
	v_fmac_f32_e32 v17, v16, v21
	s_waitcnt lgkmcnt(2)
	v_mul_f32_e32 v16, v19, v29
	v_fmac_f32_e32 v13, v12, v25
	s_waitcnt lgkmcnt(1)
	v_mul_f32_e32 v12, v15, v31
	v_fmac_f32_e32 v10, v26, v2
	s_waitcnt lgkmcnt(0)
	v_mul_f32_e32 v2, v5, v35
	v_cndmask_b32_e64 v16, v16, -v16, s[40:41]
	v_cndmask_b32_e64 v12, v12, -v12, s[40:41]
	v_cndmask_b32_e64 v5, v2, -v2, s[40:41]
	v_fmac_f32_e32 v16, v18, v23
	v_fmac_f32_e32 v12, v14, v27
	v_fmac_f32_e32 v5, v7, v4
	v_cvt_pk_bf16_f32 v2, v17, v16
	v_cvt_pk_bf16_f32 v3, v13, v12
	v_cvt_pk_bf16_f32 v4, v9, v8
	v_cvt_pk_bf16_f32 v5, v10, v5
	ds_write_b128 v107, v[2:5] offset:18432
	s_nop 0
	s_nop 0
	s_waitcnt vmcnt(0)
	ds_write2_b64 v116, v[246:247], v[198:199] offset1:1
; #define LAS __attribute__((address_space(3)))
; __device__ __forceinline__ unsigned pk2(float lo, float hi) { unsigned r; asm("v_cvt_pk_bf16_f32 %0, %1, %2" : "=v"(r) : "v"(lo), "v"(hi)); return r; }
; __device__ __forceinline__ float bflo(unsigned u) { return __uint_as_float(u << 16); }
; __device__ __forceinline__ void attn_stage(LAS unsigned char* Kl, LAS unsigned char* Vl, const bf16_t* qk, const bf16_t* Vt, int tok0, int g, int tid, const float* kgain, const float2* rope, bool do_rope) {
;     const int row = tid >> 3, piece = tid & 7;
;     const u32x4 kraw = *(const u32x4*)(qk + (size_t)(tok0 + row) * 1280 + 1024 + 64 * g + 8 * piece);
;     float y[8] = {bflo(kraw.x), bfhi(kraw.x), bflo(kraw.y), bfhi(kraw.y), bflo(kraw.z), bfhi(kraw.z), bflo(kraw.w), bfhi(kraw.w)};
;     float ss = 0.f;
; #pragma unroll
;     for (int i = 0; i < 8; ++i) ss += y[i] * y[i];
;     ss += __shfl_xor(ss, 1); ss += __shfl_xor(ss, 2); ss += __shfl_xor(ss, 4);
;     const float rs = rsqrtf(ss * (1.f / 64.f) + 1e-6f);
;     const f32x4 g0 = *(const f32x4*)(kgain + 8 * piece), g1 = *(const f32x4*)(kgain + 8 * piece + 4);
; #pragma unroll
;     for (int i = 0; i < 4; ++i) { y[i] *= rs * g0[i]; y[4 + i] *= rs * g1[i]; }
;     float py[8];
; #pragma unroll
;     for (int i = 0; i < 8; ++i) py[i] = __shfl_xor(y[i], 2);
;     if (do_rope) {
;         const int token = tok0 + row, pos = (piece < 4) ? (token >> 6) : (token & 63);
;         const float2* cs = rope + pos * 16 + 8 * (piece & 1);
; #pragma unroll
;         for (int i = 0; i < 8; ++i) { const float2 t = cs[i]; y[i] = (piece & 2) ? (py[i] * t.y + y[i] * t.x) : (y[i] * t.x - py[i] * t.y); }
;     }
;     u32x4 kv; kv.x = pk2(y[0], y[1]); kv.y = pk2(y[2], y[3]); kv.z = pk2(y[4], y[5]); kv.w = pk2(y[6], y[7]);
;     *(LAS u32x4*)(Kl + row * 144 + piece * 16) = kv;
;     const u32x4 vv = *(const u32x4*)(Vt + (size_t)(g * 64 + row) * MTOT + tok0 + 8 * piece);
;     LAS u32x2* vd = (LAS u32x2*)(Vl + row * 136 + piece * 16); vd[0] = (u32x2){vv.x, vv.y}; vd[1] = (u32x2){vv.z, vv.w};
; }
; __device__ __forceinline__ void attn_phase(const Params& P, LAS unsigned char* lds) {
;     ...
;         for (int ci = 0; ci < 5; ++ci) { const int cb = qb - 2 + ci; if (cb >= 0 && cb < SEQ / 64) attn_stage(lds + ci * KSZ, lds + VBASE + ci * VSZ, qk, Vt, 64 * cb, g, tid, P.k_gain, rope, true); }
.LBB0_730:
	s_add_i32 s19, s18, 1
	s_cmpk_lt_u32 s19, 0x100
	s_cselect_b64 s[0:1], -1, 0
	s_cmpk_gt_u32 s19, 0xff
	v_add_u32_e32 v115, 0x6600, v186
	s_cbranch_scc1 .LBB0_732
	v_lshl_add_u32 v20, s19, 6, v179
	v_mov_b64_e32 v[2:3], s[46:47]
	v_mad_i64_i32 v[2:3], s[36:37], v20, s3, v[2:3]
	v_readlane_b32 s36, v252, 30
	v_readlane_b32 s37, v252, 31
	s_lshl_b32 s36, s35, 1
	v_mov_b32_e32 v7, v1
	v_lshl_add_u64 v[2:3], v[2:3], 0, s[36:37]
	v_lshl_add_u64 v[2:3], v[2:3], 0, v[6:7]
	global_load_dwordx4 v[2:5], v[2:3], off offset:2048
	s_lshl_b32 s36, s19, 7
	s_mov_b32 s3, s37
	v_ashrrev_i32_e32 v16, 6, v20
	v_cndmask_b32_e64 v16, v183, v16, s[38:39]
	v_lshlrev_b32_e32 v16, 4, v16
	v_ashrrev_i32_e32 v17, 31, v16
	v_lshl_add_u64 v[16:17], v[16:17], 3, v[88:89]
	global_load_dwordx4 v[230:233], v[16:17], off offset:48
	global_load_dwordx4 v[234:237], v[16:17], off offset:32
	global_load_dwordx4 v[238:241], v[16:17], off offset:16
	global_load_dwordx4 v[242:245], v[16:17], off
	v_lshl_add_u64 v[18:19], v[112:113], 0, s[36:37]
	global_load_dwordx2 v[246:247], v[18:19], off
	global_load_dwordx2 v[198:199], v[18:19], off offset:8
	s_waitcnt vmcnt(6)
	v_lshlrev_b32_e32 v12, 16, v2
	v_and_b32_e32 v13, 0xffff0000, v2
	v_pk_mul_f32 v[8:9], v[12:13], v[12:13]
	v_and_b32_e32 v14, 0xffff0000, v3
	v_lshlrev_b32_e32 v15, 16, v3
	v_pk_mul_f32 v[2:3], v[14:15], v[14:15]
	v_add_f32_e32 v7, v8, v9
	v_and_b32_e32 v16, 0xffff0000, v4
	v_lshlrev_b32_e32 v17, 16, v4
	v_add_f32_e32 v3, v3, v7
	v_pk_mul_f32 v[10:11], v[16:17], v[16:17]
	v_add_f32_e32 v2, v2, v3
	v_and_b32_e32 v18, 0xffff0000, v5
	v_lshlrev_b32_e32 v19, 16, v5
	v_add_f32_e32 v2, v11, v2
	v_pk_mul_f32 v[4:5], v[18:19], v[18:19]
	v_add_f32_e32 v2, v10, v2
	v_add_f32_e32 v2, v5, v2
	v_add_f32_e32 v2, v4, v2
	ds_bpermute_b32 v3, v180, v2
	s_waitcnt lgkmcnt(0)
	v_add_f32_e32 v2, v2, v3
	ds_bpermute_b32 v3, v181, v2
	s_waitcnt lgkmcnt(0)
	v_add_f32_e32 v2, v2, v3
	ds_bpermute_b32 v3, v182, v2
	s_waitcnt lgkmcnt(0)
	v_add_f32_e32 v2, v2, v3
	v_fmamk_f32 v2, v2, 0x3c800000, v197
	v_cmp_gt_f32_e32 vcc, s2, v2
	v_mul_f32_e32 v3, 0x4b800000, v2
	v_writelane_b32 v252, s2, 30
	v_cndmask_b32_e32 v2, v2, v3, vcc
	v_rsq_f32_e32 v2, v2
	v_writelane_b32 v252, s3, 31
	v_mul_f32_e32 v3, 0x45800000, v2
	v_cndmask_b32_e32 v7, v2, v3, vcc
	v_mov_b64_e32 v[2:3], v[222:223]
	v_mov_b64_e32 v[4:5], v[224:225]
	v_mov_b64_e32 v[8:9], v[226:227]
	v_mov_b64_e32 v[10:11], v[228:229]
	s_waitcnt vmcnt(1)
	v_mul_f32_e32 v2, v2, v7
	v_mul_f32_e32 v22, v2, v17
	s_waitcnt vmcnt(0)
	v_mul_f32_e32 v2, v9, v7
	v_mul_f32_e32 v23, v2, v13
	v_mul_f32_e32 v2, v3, v7
	v_mul_f32_e32 v24, v2, v16
	v_mul_f32_e32 v2, v10, v7
	v_mul_f32_e32 v25, v2, v15
	v_mul_f32_e32 v2, v4, v7
	v_mul_f32_e32 v26, v2, v19
	v_mul_f32_e32 v2, v11, v7
	v_mul_f32_e32 v27, v2, v14
	v_mul_f32_e32 v2, v5, v7
	v_mul_f32_e32 v8, v8, v7
	v_mul_f32_e32 v7, v2, v18
	v_ashrrev_i32_e32 v2, 6, v20
	v_cndmask_b32_e64 v2, v183, v2, s[38:39]
	v_lshlrev_b32_e32 v2, 4, v2
	v_ashrrev_i32_e32 v3, 31, v2
	v_lshl_add_u64 v[16:17], v[2:3], 3, v[88:89]
	v_mul_f32_e32 v21, v8, v12
	s_waitcnt vmcnt(2)
	v_mov_b64_e32 v[2:3], v[230:231]
	v_mov_b64_e32 v[4:5], v[232:233]
	v_mov_b64_e32 v[8:9], v[234:235]
	v_mov_b64_e32 v[10:11], v[236:237]
	v_mov_b64_e32 v[12:13], v[238:239]
	v_mov_b64_e32 v[14:15], v[240:241]
	s_nop 0
	v_mov_b64_e32 v[16:17], v[242:243]
	v_mov_b64_e32 v[18:19], v[244:245]
	ds_bpermute_b32 v32, v181, v22
	ds_bpermute_b32 v33, v181, v24
	ds_bpermute_b32 v28, v181, v21
	ds_bpermute_b32 v30, v181, v25
	ds_bpermute_b32 v34, v181, v26
	ds_bpermute_b32 v29, v181, v23
	ds_bpermute_b32 v31, v181, v27
	ds_bpermute_b32 v35, v181, v7
	s_waitcnt vmcnt(3) lgkmcnt(3)
	v_mul_f32_e32 v3, v3, v34
	s_waitcnt vmcnt(2)
	v_mul_f32_e32 v9, v9, v32
	v_cndmask_b32_e64 v9, v9, -v9, s[40:41]
	v_fmac_f32_e32 v9, v8, v22
	v_mul_f32_e32 v8, v11, v33
	s_waitcnt vmcnt(0)
	v_mul_f32_e32 v17, v17, v28
	v_mul_f32_e32 v13, v13, v30
	v_cndmask_b32_e64 v8, v8, -v8, s[40:41]
	v_cndmask_b32_e64 v17, v17, -v17, s[40:41]
	v_cndmask_b32_e64 v13, v13, -v13, s[40:41]
	v_fmac_f32_e32 v8, v10, v24
	v_cndmask_b32_e64 v10, v3, -v3, s[40:41]
	v_fmac_f32_e32 v17, v16, v21
	s_waitcnt lgkmcnt(2)
	v_mul_f32_e32 v16, v19, v29
	v_fmac_f32_e32 v13, v12, v25
	s_waitcnt lgkmcnt(1)
	v_mul_f32_e32 v12, v15, v31
	v_fmac_f32_e32 v10, v26, v2
	s_waitcnt lgkmcnt(0)
	v_mul_f32_e32 v2, v5, v35
	v_cndmask_b32_e64 v16, v16, -v16, s[40:41]
	v_cndmask_b32_e64 v12, v12, -v12, s[40:41]
	v_cndmask_b32_e64 v5, v2, -v2, s[40:41]
	v_fmac_f32_e32 v16, v18, v23
	v_fmac_f32_e32 v12, v14, v27
	v_fmac_f32_e32 v5, v7, v4
	v_cvt_pk_bf16_f32 v2, v17, v16
	v_cvt_pk_bf16_f32 v3, v13, v12
	v_cvt_pk_bf16_f32 v4, v9, v8
	v_cvt_pk_bf16_f32 v5, v10, v5
	ds_write_b128 v107, v[2:5] offset:27648
	s_nop 0
	s_nop 0
	s_waitcnt vmcnt(0)
	ds_write2_b64 v115, v[246:247], v[198:199] offset1:1
; #define LAS __attribute__((address_space(3)))
; __device__ __forceinline__ unsigned pk2(float lo, float hi) { unsigned r; asm("v_cvt_pk_bf16_f32 %0, %1, %2" : "=v"(r) : "v"(lo), "v"(hi)); return r; }
; __device__ __forceinline__ float bflo(unsigned u) { return __uint_as_float(u << 16); }
; __device__ __forceinline__ void attn_stage(LAS unsigned char* Kl, LAS unsigned char* Vl, const bf16_t* qk, const bf16_t* Vt, int tok0, int g, int tid, const float* kgain, const float2* rope, bool do_rope) {
;     const int row = tid >> 3, piece = tid & 7;
;     const u32x4 kraw = *(const u32x4*)(qk + (size_t)(tok0 + row) * 1280 + 1024 + 64 * g + 8 * piece);
;     float y[8] = {bflo(kraw.x), bfhi(kraw.x), bflo(kraw.y), bfhi(kraw.y), bflo(kraw.z), bfhi(kraw.z), bflo(kraw.w), bfhi(kraw.w)};
;     float ss = 0.f;
; #pragma unroll
;     for (int i = 0; i < 8; ++i) ss += y[i] * y[i];
;     ss += __shfl_xor(ss, 1); ss += __shfl_xor(ss, 2); ss += __shfl_xor(ss, 4);
;     const float rs = rsqrtf(ss * (1.f / 64.f) + 1e-6f);
;     const f32x4 g0 = *(const f32x4*)(kgain + 8 * piece), g1 = *(const f32x4*)(kgain + 8 * piece + 4);
; #pragma unroll
;     for (int i = 0; i < 4; ++i) { y[i] *= rs * g0[i]; y[4 + i] *= rs * g1[i]; }
;     float py[8];
; #pragma unroll
;     for (int i = 0; i < 8; ++i) py[i] = __shfl_xor(y[i], 2);
;     if (do_rope) {
;         const int token = tok0 + row, pos = (piece < 4) ? (token >> 6) : (token & 63);
;         const float2* cs = rope + pos * 16 + 8 * (piece & 1);
; #pragma unroll
;         for (int i = 0; i < 8; ++i) { const float2 t = cs[i]; y[i] = (piece & 2) ? (py[i] * t.y + y[i] * t.x) : (y[i] * t.x - py[i] * t.y); }
;     }
;     u32x4 kv; kv.x = pk2(y[0], y[1]); kv.y = pk2(y[2], y[3]); kv.z = pk2(y[4], y[5]); kv.w = pk2(y[6], y[7]);
;     *(LAS u32x4*)(Kl + row * 144 + piece * 16) = kv;
;     const u32x4 vv = *(const u32x4*)(Vt + (size_t)(g * 64 + row) * MTOT + tok0 + 8 * piece);
;     LAS u32x2* vd = (LAS u32x2*)(Vl + row * 136 + piece * 16); vd[0] = (u32x2){vv.x, vv.y}; vd[1] = (u32x2){vv.z, vv.w};
; }
; __device__ __forceinline__ void attn_phase(const Params& P, LAS unsigned char* lds) {
;     ...
;         for (int ci = 0; ci < 5; ++ci) { const int cb = qb - 2 + ci; if (cb >= 0 && cb < SEQ / 64) attn_stage(lds + ci * KSZ, lds + VBASE + ci * VSZ, qk, Vt, 64 * cb, g, tid, P.k_gain, rope, true); }
.LBB0_732:
	s_add_i32 s18, s18, 2
	s_cmpk_lt_u32 s18, 0x100
	s_movk_i32 s3, 0xa00
	s_mov_b32 s2, 0x800000
	s_cselect_b64 s[48:49], -1, 0
	s_cmpk_gt_u32 s18, 0xff
	s_cbranch_scc1 .LBB0_734
	v_readlane_b32 s36, v250, 31
	v_readlane_b32 s37, v250, 32
	v_lshl_add_u32 v18, s18, 6, v179
	v_mov_b32_e32 v7, v1
	v_mov_b64_e32 v[2:3], s[36:37]
	v_mad_i64_i32 v[2:3], s[36:37], v18, s3, v[2:3]
	v_readlane_b32 s36, v252, 30
	v_readlane_b32 s37, v252, 31
	s_lshl_b32 s36, s35, 1
	s_mov_b32 s3, s37
	v_lshl_add_u64 v[2:3], v[2:3], 0, s[36:37]
	v_lshl_add_u64 v[2:3], v[2:3], 0, v[6:7]
	global_load_dwordx4 v[2:5], v[2:3], off offset:2048
	s_lshl_b32 s36, s18, 7
	v_ashrrev_i32_e32 v14, 6, v18
	v_cndmask_b32_e64 v14, v183, v14, s[38:39]
	v_lshlrev_b32_e32 v14, 4, v14
	v_ashrrev_i32_e32 v15, 31, v14
	v_lshl_add_u64 v[14:15], v[14:15], 3, v[88:89]
	global_load_dwordx4 v[230:233], v[14:15], off offset:48
	global_load_dwordx4 v[234:237], v[14:15], off offset:32
	global_load_dwordx4 v[238:241], v[14:15], off offset:16
	global_load_dwordx4 v[242:245], v[14:15], off
	v_lshl_add_u64 v[16:17], v[112:113], 0, s[36:37]
	global_load_dwordx2 v[246:247], v[16:17], off
	global_load_dwordx2 v[198:199], v[16:17], off offset:8
	s_waitcnt vmcnt(6)
	v_lshlrev_b32_e32 v10, 16, v2
	v_and_b32_e32 v11, 0xffff0000, v2
	v_pk_mul_f32 v[6:7], v[10:11], v[10:11]
	v_and_b32_e32 v12, 0xffff0000, v3
	v_lshlrev_b32_e32 v13, 16, v3
	v_pk_mul_f32 v[2:3], v[12:13], v[12:13]
	v_add_f32_e32 v6, v6, v7
	v_and_b32_e32 v14, 0xffff0000, v4
	v_lshlrev_b32_e32 v15, 16, v4
	v_add_f32_e32 v3, v3, v6
	v_pk_mul_f32 v[8:9], v[14:15], v[14:15]
	v_add_f32_e32 v2, v2, v3
	v_and_b32_e32 v16, 0xffff0000, v5
	v_lshlrev_b32_e32 v17, 16, v5
	v_add_f32_e32 v2, v9, v2
	v_pk_mul_f32 v[4:5], v[16:17], v[16:17]
	v_add_f32_e32 v2, v8, v2
	v_add_f32_e32 v2, v5, v2
	v_add_f32_e32 v2, v4, v2
	ds_bpermute_b32 v3, v180, v2
	s_waitcnt lgkmcnt(0)
	v_add_f32_e32 v2, v2, v3
	ds_bpermute_b32 v3, v181, v2
	s_waitcnt lgkmcnt(0)
	v_add_f32_e32 v2, v2, v3
	ds_bpermute_b32 v3, v182, v2
	s_waitcnt lgkmcnt(0)
	v_add_f32_e32 v2, v2, v3
	v_fmamk_f32 v2, v2, 0x3c800000, v197
	v_cmp_gt_f32_e32 vcc, s2, v2
	v_mul_f32_e32 v3, 0x4b800000, v2
	v_writelane_b32 v252, s2, 30
	v_cndmask_b32_e32 v2, v2, v3, vcc
	v_rsq_f32_e32 v2, v2
	v_writelane_b32 v252, s3, 31
	v_mul_f32_e32 v3, 0x45800000, v2
	v_cndmask_b32_e32 v19, v2, v3, vcc
	v_mov_b64_e32 v[2:3], v[222:223]
	v_mov_b64_e32 v[4:5], v[224:225]
	v_mov_b64_e32 v[6:7], v[226:227]
	v_mov_b64_e32 v[8:9], v[228:229]
	s_waitcnt vmcnt(1)
	v_mul_f32_e32 v2, v2, v19
	v_mul_f32_e32 v21, v2, v15
	s_waitcnt vmcnt(0)
	v_mul_f32_e32 v2, v7, v19
	v_mul_f32_e32 v22, v2, v11
	v_mul_f32_e32 v2, v3, v19
	v_mul_f32_e32 v23, v2, v14
	v_mul_f32_e32 v2, v8, v19
	v_mul_f32_e32 v24, v2, v13
	v_mul_f32_e32 v2, v4, v19
	v_mul_f32_e32 v25, v2, v17
	v_mul_f32_e32 v2, v9, v19
	v_mul_f32_e32 v26, v2, v12
	v_mul_f32_e32 v2, v5, v19
	v_mul_f32_e32 v6, v6, v19
	v_mul_f32_e32 v19, v2, v16
	v_ashrrev_i32_e32 v2, 6, v18
	v_cndmask_b32_e64 v2, v183, v2, s[38:39]
	v_lshlrev_b32_e32 v2, 4, v2
	v_ashrrev_i32_e32 v3, 31, v2
	v_lshl_add_u64 v[14:15], v[2:3], 3, v[88:89]
	v_mul_f32_e32 v20, v6, v10
	s_waitcnt vmcnt(2)
	v_mov_b64_e32 v[2:3], v[230:231]
	v_mov_b64_e32 v[4:5], v[232:233]
	v_mov_b64_e32 v[6:7], v[234:235]
	v_mov_b64_e32 v[8:9], v[236:237]
	v_mov_b64_e32 v[10:11], v[238:239]
	v_mov_b64_e32 v[12:13], v[240:241]
	s_nop 0
	v_mov_b64_e32 v[14:15], v[242:243]
	v_mov_b64_e32 v[16:17], v[244:245]
	ds_bpermute_b32 v31, v181, v21
	ds_bpermute_b32 v32, v181, v23
	ds_bpermute_b32 v27, v181, v20
	ds_bpermute_b32 v29, v181, v24
	ds_bpermute_b32 v33, v181, v25
	ds_bpermute_b32 v28, v181, v22
	ds_bpermute_b32 v30, v181, v26
	ds_bpermute_b32 v34, v181, v19
	s_waitcnt vmcnt(3) lgkmcnt(3)
	v_mul_f32_e32 v3, v3, v33
	s_waitcnt vmcnt(2)
	v_mul_f32_e32 v7, v7, v31
	v_cndmask_b32_e64 v7, v7, -v7, s[40:41]
	v_fmac_f32_e32 v7, v6, v21
	v_mul_f32_e32 v6, v9, v32
	s_waitcnt vmcnt(0)
	v_mul_f32_e32 v15, v15, v27
	v_mul_f32_e32 v11, v11, v29
	v_cndmask_b32_e64 v6, v6, -v6, s[40:41]
	v_cndmask_b32_e64 v15, v15, -v15, s[40:41]
	v_cndmask_b32_e64 v11, v11, -v11, s[40:41]
	v_fmac_f32_e32 v6, v8, v23
	v_cndmask_b32_e64 v8, v3, -v3, s[40:41]
	v_fmac_f32_e32 v15, v14, v20
	s_waitcnt lgkmcnt(2)
	v_mul_f32_e32 v14, v17, v28
	v_fmac_f32_e32 v11, v10, v24
	s_waitcnt lgkmcnt(1)
	v_mul_f32_e32 v10, v13, v30
	v_fmac_f32_e32 v8, v25, v2
	s_waitcnt lgkmcnt(0)
	v_mul_f32_e32 v2, v5, v34
	v_cndmask_b32_e64 v14, v14, -v14, s[40:41]
	v_cndmask_b32_e64 v10, v10, -v10, s[40:41]
	v_cndmask_b32_e64 v5, v2, -v2, s[40:41]
	v_fmac_f32_e32 v14, v16, v22
	v_fmac_f32_e32 v10, v12, v26
	v_fmac_f32_e32 v5, v19, v4
	v_cvt_pk_bf16_f32 v2, v15, v14
	v_cvt_pk_bf16_f32 v3, v11, v10
	v_cvt_pk_bf16_f32 v4, v7, v6
	v_cvt_pk_bf16_f32 v5, v8, v5
	ds_write_b128 v107, v[2:5] offset:36864
	s_nop 0
	s_nop 0
	v_add_u32_e32 v6, 0x8800, v186
	s_waitcnt vmcnt(0)
	ds_write2_b64 v6, v[246:247], v[198:199] offset1:1

; #define PG8_STAGE(bufoff, gbase, voff) do { _Pragma("unroll") for (int _i = 0; _i < 2; ++_i) \
;         __builtin_amdgcn_global_load_lds((const unsigned*)((const char*)(gbase) + (voff)[_i]), (LAS unsigned*)(lds + (bufoff) + ldsw + _i * 8192), 16, 0, 0); } while (0)
; #define PG8_STAGE_A(bufoff, gbase, h, vv) do { if constexpr (GATHER) { _Pragma("unroll") for (int _i = 0; _i < 2; ++_i) \
;         __builtin_amdgcn_global_load_lds((const unsigned*)((const char*)(gbase) + (vv)[h][_i]), (LAS unsigned*)(lds + (bufoff) + ldsw + _i * 8192), 16, 0, 0); } \
;         else { PG8_STAGE(bufoff, (gbase) + (h) * hstepA, voffA); } } while (0)
; #define PG8_WAIT_V(n) asm volatile("s_waitcnt vmcnt(" #n ")" ::: "memory")
; #define PG8_BAR __builtin_amdgcn_s_barrier()
; template <class Epi, class Sched>
; __device__ __forceinline__ void gemm_phase(LAS unsigned char* lds, const int K, const int lda, const int ldb, const Sched& S, const Epi& E) {
;     ...
;     PG8_STAGE(PG8_SB(0, 0), cB, voffB); PG8_STAGE_A(PG8_SA(0, 0), cA, 0, vcur); PG8_STAGE(PG8_SB(0, 1), cB + hstepB, voffB); PG8_STAGE_A(PG8_SA(0, 1), cA, 1, vcur);
;     if (wr == 1) PG8_BAR;
;     PG8_WAIT_V(4); PG8_BAR;
;     PG8_STAGE(PG8_SB(1, 0), cB + kstep, voffB); PG8_STAGE_A(PG8_SA(1, 0), cA + kstep, 0, vcur); PG8_STAGE(PG8_SB(1, 1), cB + hstepB + kstep, voffB);
;     PG8_WAIT_V(6); PG8_BAR;
.LBB0_753:
	s_sext_i32_i16 s67, s0
	s_and_b64 s[0:1], s[10:11], exec
	s_mov_b32 s0, 0x2dcf9000
	s_cselect_b32 s0, s0, 0x30599000
	s_add_u32 s0, s28, s0
	v_lshrrev_b32_e32 v18, 1, v14
	s_addc_u32 s1, s29, 0
	v_and_b32_e32 v18, 24, v18
	s_and_b64 s[6:7], s[10:11], exec
	s_movk_i32 s2, 0x500
	v_and_b32_e32 v17, 15, v14
	v_lshlrev_b32_e32 v19, 1, v18
	v_lshlrev_b32_e32 v14, 2, v14
	s_cselect_b32 s62, s2, 0x4100
	v_lshl_or_b32 v142, s4, 6, v17
	v_lshl_or_b32 v17, v17, 6, v19
	s_lshl_b32 s2, s4, 13
	v_and_b32_e32 v14, 32, v14
	v_bitop3_b32 v19, v17, s2, v14 bitop3:0xde
	s_lshl_b32 s2, s5, 5
	s_and_b32 s2, s2, 0x60
	s_add_i32 m0, s9, 0x18000
	v_lshl_add_u64 v[8:9], v[8:9], 0, s[64:65]
	s_lshl_b32 s3, s2, 7
	s_waitcnt vmcnt(4)
	s_barrier
	global_load_lds_dwordx4 v[8:9], off
	v_lshl_add_u64 v[6:7], v[6:7], 0, s[64:65]
	s_add_i32 m0, s9, 0x1a000
	s_add_i32 s63, s9, 0x8000
	s_add_i32 s66, s9, 0xa000
	global_load_lds_dwordx4 v[6:7], off
	v_lshl_add_u64 v[4:5], v[4:5], 0, s[64:65]
	s_mov_b32 m0, s63
	s_add_u32 s4, s34, 0x40080
	global_load_lds_dwordx4 v[4:5], off
	v_lshl_add_u64 v[2:3], v[2:3], 0, s[64:65]
	s_mov_b32 m0, s66
	s_addc_u32 s5, s35, 0
	global_load_lds_dwordx4 v[2:3], off
	s_add_i32 m0, s9, 0x1c000
	v_lshl_add_u64 v[2:3], s[4:5], 0, v[0:1]
	global_load_lds_dwordx4 v[2:3], off
	v_lshl_add_u64 v[2:3], s[4:5], 0, v[134:135]
	s_add_i32 m0, s9, 0x1e000
	s_mov_b32 s60, 0
	global_load_lds_dwordx4 v[2:3], off
	v_lshlrev_b32_e32 v2, 14, v10
	v_and_b32_e32 v2, 0xffff8000, v2
	v_lshl_add_u32 v2, v11, 11, v2
	v_and_b32_e32 v3, 1, v10
	v_lshl_or_b32 v2, v3, 6, v2
	v_lshl_add_u32 v136, v12, 1, v2
	v_lshlrev_b32_e32 v2, 14, v13
	v_and_b32_e32 v2, 0xffff8000, v2
	s_waitcnt vmcnt(6)
	v_lshl_add_u32 v2, v15, 11, v2
	v_and_b32_e32 v3, 1, v13
	v_lshl_or_b32 v2, v3, 6, v2
	v_bitop3_b32 v143, v17, s3, v14 bitop3:0xde
	v_or_b32_e32 v144, s2, v18
	v_mov_b32_e32 v137, v1
	v_lshl_add_u32 v138, v16, 1, v2
	v_mov_b32_e32 v139, v1
	v_add_u32_e32 v145, 0, v19
	s_mov_b64 s[12:13], s[16:17]
	s_mov_b64 s[14:15], s[34:35]
	s_barrier
	s_nop 0

; #define PG8_STAGE(bufoff, gbase, voff) do { _Pragma("unroll") for (int _i = 0; _i < 2; ++_i) \
;         __builtin_amdgcn_global_load_lds((const unsigned*)((const char*)(gbase) + (voff)[_i]), (LAS unsigned*)(lds + (bufoff) + ldsw + _i * 8192), 16, 0, 0); } while (0)
; #define PG8_STAGE_A(bufoff, gbase, h, vv) do { if constexpr (GATHER) { _Pragma("unroll") for (int _i = 0; _i < 2; ++_i) \
;         __builtin_amdgcn_global_load_lds((const unsigned*)((const char*)(gbase) + (vv)[h][_i]), (LAS unsigned*)(lds + (bufoff) + ldsw + _i * 8192), 16, 0, 0); } \
;         else { PG8_STAGE(bufoff, (gbase) + (h) * hstepA, voffA); } } while (0)
; #define PG8_WAIT_V(n) asm volatile("s_waitcnt vmcnt(" #n ")" ::: "memory")
; #define PG8_BAR __builtin_amdgcn_s_barrier()
; template <class Epi, class Sched>
; __device__ __forceinline__ void gemm_phase(LAS unsigned char* lds, const int K, const int lda, const int ldb, const Sched& S, const Epi& E) {
;     ...
;     PG8_STAGE(PG8_SB(0, 0), cB, voffB); PG8_STAGE_A(PG8_SA(0, 0), cA, 0, vcur); PG8_STAGE(PG8_SB(0, 1), cB + hstepB, voffB); PG8_STAGE_A(PG8_SA(0, 1), cA, 1, vcur);
;     if (wr == 1) PG8_BAR;
;     PG8_WAIT_V(4); PG8_BAR;
;     PG8_STAGE(PG8_SB(1, 0), cB + kstep, voffB); PG8_STAGE_A(PG8_SA(1, 0), cA + kstep, 0, vcur); PG8_STAGE(PG8_SB(1, 1), cB + hstepB + kstep, voffB);
;     PG8_WAIT_V(6); PG8_BAR;
.LBB0_873:
	v_lshrrev_b32_e32 v18, 1, v6
	v_and_b32_e32 v18, 24, v18
	v_and_b32_e32 v9, 15, v6
	v_lshlrev_b32_e32 v19, 1, v18
	v_lshlrev_b32_e32 v6, 2, v6
	s_sext_i32_i16 s52, s0
	v_lshl_or_b32 v142, s1, 6, v9
	v_lshl_or_b32 v9, v9, 6, v19
	s_lshl_b32 s0, s1, 13
	v_and_b32_e32 v6, 32, v6
	v_lshl_add_u64 v[10:11], s[16:17], 0, v[0:1]
	v_mov_b32_e32 v135, v1
	v_bitop3_b32 v19, v9, s0, v6 bitop3:0xde
	s_lshl_b32 s0, s4, 5
	v_lshl_add_u64 v[12:13], s[16:17], 0, v[134:135]
	v_mov_b32_e32 v131, v1
	s_and_b32 s2, s0, 0x60
	s_add_i32 m0, s13, 0x18000
	v_lshl_add_u64 v[10:11], v[10:11], 0, s[64:65]
	v_lshl_add_u64 v[14:15], s[14:15], 0, v[130:131]
	v_mov_b32_e32 v133, v1
	s_lshl_b32 s0, s2, 7
	s_waitcnt vmcnt(4)
	s_barrier
	global_load_lds_dwordx4 v[10:11], off
	v_lshl_add_u64 v[10:11], v[12:13], 0, s[64:65]
	s_add_i32 m0, s13, 0x1a000
	s_add_i32 s47, s13, 0x8000
	s_add_i32 s48, s13, 0xa000
	v_lshl_add_u64 v[16:17], s[14:15], 0, v[132:133]
	v_bitop3_b32 v143, v9, s0, v6 bitop3:0xde
	global_load_lds_dwordx4 v[10:11], off
	v_lshl_add_u64 v[10:11], v[14:15], 0, s[64:65]
	s_mov_b32 m0, s47
	s_add_u32 s0, s16, 0x40080
	global_load_lds_dwordx4 v[10:11], off
	v_lshl_add_u64 v[10:11], v[16:17], 0, s[64:65]
	s_mov_b32 m0, s48
	s_addc_u32 s1, s17, 0
	global_load_lds_dwordx4 v[10:11], off
	s_add_i32 m0, s13, 0x1c000
	v_lshl_add_u64 v[10:11], s[0:1], 0, v[0:1]
	global_load_lds_dwordx4 v[10:11], off
	v_lshl_add_u64 v[10:11], s[0:1], 0, v[134:135]
	s_add_i32 m0, s13, 0x1e000
	v_lshlrev_b32_e32 v6, 14, v2
	global_load_lds_dwordx4 v[10:11], off
	v_and_b32_e32 v6, 0xffff8000, v6
	v_lshl_add_u32 v3, v3, 11, v6
	v_and_b32_e32 v2, 1, v2
	v_lshl_or_b32 v2, v2, 6, v3
	v_lshl_add_u32 v136, v4, 1, v2
	v_lshlrev_b32_e32 v2, 14, v5
	v_and_b32_e32 v2, 0xffff8000, v2
	s_waitcnt vmcnt(6)
	v_lshl_add_u32 v2, v7, 11, v2
	v_and_b32_e32 v3, 1, v5
	v_lshl_or_b32 v2, v3, 6, v2
	v_or_b32_e32 v144, s2, v18
	v_mov_b32_e32 v137, v1
	v_lshl_add_u32 v138, v8, 1, v2
	v_mov_b32_e32 v139, v1
	s_mov_b32 s49, 0
	v_add_u32_e32 v145, 0, v19
	s_mov_b64 s[8:9], s[14:15]
	s_mov_b64 s[10:11], s[16:17]
	s_barrier
	s_nop 0

; #define PG8_STAGE(bufoff, gbase, voff) do { _Pragma("unroll") for (int _i = 0; _i < 2; ++_i) \
;         __builtin_amdgcn_global_load_lds((const unsigned*)((const char*)(gbase) + (voff)[_i]), (LAS unsigned*)(lds + (bufoff) + ldsw + _i * 8192), 16, 0, 0); } while (0)
; #define PG8_STAGE_A(bufoff, gbase, h, vv) do { if constexpr (GATHER) { _Pragma("unroll") for (int _i = 0; _i < 2; ++_i) \
;         __builtin_amdgcn_global_load_lds((const unsigned*)((const char*)(gbase) + (vv)[h][_i]), (LAS unsigned*)(lds + (bufoff) + ldsw + _i * 8192), 16, 0, 0); } \
;         else { PG8_STAGE(bufoff, (gbase) + (h) * hstepA, voffA); } } while (0)
; #define PG8_WAIT_V(n) asm volatile("s_waitcnt vmcnt(" #n ")" ::: "memory")
; #define PG8_BAR __builtin_amdgcn_s_barrier()
; template <class Epi, class Sched>
; __device__ __forceinline__ void gemm_phase(LAS unsigned char* lds, const int K, const int lda, const int ldb, const Sched& S, const Epi& E) {
;     ...
;     PG8_STAGE(PG8_SB(0, 0), cB, voffB); PG8_STAGE_A(PG8_SA(0, 0), cA, 0, vcur); PG8_STAGE(PG8_SB(0, 1), cB + hstepB, voffB); PG8_STAGE_A(PG8_SA(0, 1), cA, 1, vcur);
;     if (wr == 1) PG8_BAR;
;     PG8_WAIT_V(4); PG8_BAR;
;     PG8_STAGE(PG8_SB(1, 0), cB + kstep, voffB); PG8_STAGE_A(PG8_SA(1, 0), cA + kstep, 0, vcur); PG8_STAGE(PG8_SB(1, 1), cB + hstepB + kstep, voffB);
;     PG8_WAIT_V(6); PG8_BAR;
.LBB0_964:
	v_mov_b32_e32 v133, v1
	v_lshl_add_u64 v[10:11], s[16:17], 0, v[132:133]
	v_mov_b32_e32 v137, v1
	s_lshl_b32 s2, s4, 5
	v_lshl_add_u64 v[12:13], s[16:17], 0, v[136:137]
	v_mov_b32_e32 v131, v1
	s_and_b32 s2, s2, 0x60
	s_add_i32 m0, s39, 0x18000
	v_lshl_add_u64 v[10:11], v[10:11], 0, s[64:65]
	v_lshl_add_u64 v[14:15], s[14:15], 0, v[130:131]
	v_mov_b32_e32 v135, v1
	s_lshl_b32 s43, s1, 6
	s_lshl_b32 s1, s1, 13
	s_lshl_b32 s3, s2, 7
	s_waitcnt vmcnt(4)
	s_barrier
	global_load_lds_dwordx4 v[10:11], off
	v_lshl_add_u64 v[10:11], v[12:13], 0, s[64:65]
	s_add_i32 m0, s39, 0x1a000
	s_add_i32 s44, s39, 0x8000
	s_add_i32 s45, s39, 0xa000
	v_lshl_add_u64 v[16:17], s[14:15], 0, v[134:135]
	global_load_lds_dwordx4 v[10:11], off
	v_lshl_add_u64 v[10:11], v[14:15], 0, s[64:65]
	s_mov_b32 m0, s44
	s_add_u32 s4, s16, 0x40080
	global_load_lds_dwordx4 v[10:11], off
	v_lshl_add_u64 v[10:11], v[16:17], 0, s[64:65]
	s_mov_b32 m0, s45
	s_addc_u32 s5, s17, 0
	global_load_lds_dwordx4 v[10:11], off
	s_add_i32 m0, s39, 0x1c000
	v_lshl_add_u64 v[10:11], s[4:5], 0, v[132:133]
	global_load_lds_dwordx4 v[10:11], off
	v_lshl_add_u64 v[10:11], s[4:5], 0, v[136:137]
	s_add_i32 m0, s39, 0x1e000
	v_lshrrev_b32_e32 v9, 1, v0
	global_load_lds_dwordx4 v[10:11], off
	v_and_b32_e32 v9, 24, v9
	v_and_b32_e32 v139, 15, v0
	v_lshlrev_b32_e32 v10, 1, v9
	v_lshlrev_b32_e32 v0, 2, v0
	v_lshl_or_b32 v10, v139, 6, v10
	v_and_b32_e32 v0, 32, v0
	v_bitop3_b32 v11, v10, s1, v0 bitop3:0xde
	v_bitop3_b32 v146, v10, s3, v0 bitop3:0xde
	v_mul_f32_e32 v0, 0x4f7ffffe, v2
	v_cvt_u32_f32_e32 v0, v0
	v_or_b32_e32 v138, s2, v9
	v_and_b32_e32 v2, 1, v3
	s_sub_i32 s1, 0, s20
	v_readfirstlane_b32 s2, v0
	v_lshlrev_b32_e32 v0, 14, v3
	v_and_b32_e32 v0, 0xffff8000, v0
	v_lshl_add_u32 v0, v4, 11, v0
	v_lshl_or_b32 v0, v2, 6, v0
	v_lshl_add_u32 v140, v5, 1, v0
	v_lshlrev_b32_e32 v0, 14, v6
	v_and_b32_e32 v0, 0xffff8000, v0
	s_waitcnt vmcnt(6)
	s_mul_i32 s1, s1, s2
	v_lshl_add_u32 v0, v7, 11, v0
	v_and_b32_e32 v2, 1, v6
	s_mul_hi_u32 s1, s2, s1
	v_lshl_or_b32 v0, v2, 6, v0
	s_mov_b32 s46, 0
	s_add_i32 s47, s2, s1
	v_mov_b32_e32 v141, v1
	v_lshl_add_u32 v142, v8, 1, v0
	v_mov_b32_e32 v143, v1
	v_add_u32_e32 v147, 0, v11
	s_mov_b64 s[12:13], s[16:17]
	s_mov_b64 s[10:11], s[14:15]
	s_barrier
	s_nop 0
	s_branch .LBB0_966
